# prep loop: no per-tile store drain (hoisted mu load, counted vmcnt, global ops); GEMM1 epilogue: 8 SS loads batched, one wait
# speedup vs baseline: 1.0293x; 1.0031x over previous
; __device__ __forceinline__ unsigned pk2(float lo, float hi) { return f2bf(lo) | (f2bf(hi) << 16); }
; __device__ __forceinline__ void phase_prep(const Args& A, const Ctx& C0, int l) {
;     ...
;     { const int fr = C.lane & 15, fq = C.lane >> 4;
; #pragma unroll
;       for (int mat = 0; mat < 2; ++mat) { const float* W = A.in[mat ? I_AUP : I_WUP] + (size_t)l * 64 * 512 + head * 64 + fr;
; #pragma unroll
;           for (int ct = 0; ct < 4; ++ct)
; #pragma unroll
;               for (int ks = 0; ks < 2; ++ks) { const float* p = W + (size_t)(ks * 32 + 8 * fq) * 512 + ct * 16;
;                   union { bf16x8 v; unsigned w[4]; } f;
; #pragma unroll
;                   for (int e = 0; e < 4; ++e) f.w[e] = pk2(p[(2 * e) * 512], p[(2 * e + 1) * 512]);
;                   wfr[mat][ct][ks] = f.v; } } }
.LBB0_43:
	v_and_b32_e32 v166, 63, v94
	s_andn2_b64 vcc, exec, s[40:41]
	s_cbranch_vccnz .LBB0_116
	s_waitcnt vmcnt(0)
	v_bfe_u32 v167, v19, 16, 1
	v_add3_u32 v19, v19, v167, s33
	v_bfe_u32 v167, v18, 16, 1
	v_lshrrev_b32_e32 v19, 16, v19
	v_add3_u32 v18, v18, v167, s33
	v_and_or_b32 v18, v18, s96, v19
	v_bfe_u32 v19, v159, 16, 1
	v_add3_u32 v19, v159, v19, s33
	v_bfe_u32 v159, v20, 16, 1
	v_lshrrev_b32_e32 v19, 16, v19
	v_add3_u32 v20, v20, v159, s33
	v_and_or_b32 v19, v20, s96, v19
	v_bfe_u32 v20, v158, 16, 1
	v_add3_u32 v20, v158, v20, s33
	v_bfe_u32 v158, v22, 16, 1
	v_lshrrev_b32_e32 v20, 16, v20
	v_add3_u32 v22, v22, v158, s33
	v_and_or_b32 v20, v22, s96, v20
	v_bfe_u32 v22, v21, 16, 1
	v_add3_u32 v21, v21, v22, s33
	v_bfe_u32 v22, v164, 16, 1
	v_lshrrev_b32_e32 v21, 16, v21
	v_add3_u32 v22, v164, v22, s33
	v_and_or_b32 v21, v22, s96, v21
	v_bfe_u32 v22, v161, 16, 1
	v_add3_u32 v22, v161, v22, s33
	v_bfe_u32 v158, v162, 16, 1
	v_lshrrev_b32_e32 v22, 16, v22
	v_add3_u32 v158, v162, v158, s33
	v_and_or_b32 v22, v158, s96, v22
	v_bfe_u32 v158, v23, 16, 1
	v_add3_u32 v23, v23, v158, s33
	v_bfe_u32 v158, v165, 16, 1
	v_lshrrev_b32_e32 v23, 16, v23
	v_add3_u32 v158, v165, v158, s33
	v_and_or_b32 v23, v158, s96, v23
	v_bfe_u32 v158, v25, 16, 1
	v_add3_u32 v25, v25, v158, s33
	v_bfe_u32 v158, v24, 16, 1
	v_lshrrev_b32_e32 v25, 16, v25
	v_add3_u32 v24, v24, v158, s33
	v_and_or_b32 v24, v24, s96, v25
	v_bfe_u32 v25, v160, 16, 1
	v_add3_u32 v25, v160, v25, s33
	v_bfe_u32 v158, v163, 16, 1
	v_lshrrev_b32_e32 v25, 16, v25
	v_add3_u32 v158, v163, v158, s33
	v_and_or_b32 v25, v158, s96, v25
	v_bfe_u32 v158, v27, 16, 1
	v_add3_u32 v27, v27, v158, s33
	v_bfe_u32 v158, v26, 16, 1
	v_lshrrev_b32_e32 v27, 16, v27
	v_add3_u32 v26, v26, v158, s33
	v_and_or_b32 v26, v26, s96, v27
	v_bfe_u32 v27, v29, 16, 1
	v_add3_u32 v27, v29, v27, s33
	v_bfe_u32 v29, v28, 16, 1
	v_lshrrev_b32_e32 v27, 16, v27
	v_add3_u32 v28, v28, v29, s33
	v_and_or_b32 v27, v28, s96, v27
	v_bfe_u32 v28, v31, 16, 1
	v_add3_u32 v28, v31, v28, s33
	v_bfe_u32 v29, v30, 16, 1
	v_lshrrev_b32_e32 v28, 16, v28
	v_add3_u32 v29, v30, v29, s33
	v_and_or_b32 v28, v29, s96, v28
	v_bfe_u32 v29, v157, 16, 1
	v_add3_u32 v29, v157, v29, s33
	v_bfe_u32 v30, v156, 16, 1
	v_lshrrev_b32_e32 v29, 16, v29
	v_add3_u32 v30, v156, v30, s33
	v_and_or_b32 v29, v30, s96, v29
	v_bfe_u32 v30, v154, 16, 1
	v_add3_u32 v30, v154, v30, s33
	v_bfe_u32 v31, v153, 16, 1
	v_lshrrev_b32_e32 v30, 16, v30
	v_add3_u32 v31, v153, v31, s33
	v_and_or_b32 v30, v31, s96, v30
	v_bfe_u32 v31, v151, 16, 1
	v_add3_u32 v31, v151, v31, s33
	v_bfe_u32 v151, v155, 16, 1
	v_lshrrev_b32_e32 v31, 16, v31
	v_add3_u32 v151, v155, v151, s33
	v_and_or_b32 v31, v151, s96, v31
	v_bfe_u32 v151, v33, 16, 1
	v_add3_u32 v33, v33, v151, s33
	v_bfe_u32 v151, v32, 16, 1
	v_lshrrev_b32_e32 v33, 16, v33
	v_add3_u32 v32, v32, v151, s33
	v_and_or_b32 v32, v32, s96, v33
	v_bfe_u32 v33, v150, 16, 1
	v_add3_u32 v33, v150, v33, s33
	v_bfe_u32 v150, v152, 16, 1
	v_lshrrev_b32_e32 v33, 16, v33
	v_add3_u32 v150, v152, v150, s33
	v_and_or_b32 v33, v150, s96, v33
	v_bfe_u32 v150, v35, 16, 1
	v_add3_u32 v35, v35, v150, s33
	v_bfe_u32 v150, v34, 16, 1
	v_lshrrev_b32_e32 v35, 16, v35
	v_add3_u32 v34, v34, v150, s33
	v_and_or_b32 v34, v34, s96, v35
	v_bfe_u32 v35, v37, 16, 1
	v_add3_u32 v35, v37, v35, s33
	v_bfe_u32 v37, v36, 16, 1
	v_lshrrev_b32_e32 v35, 16, v35
	v_add3_u32 v36, v36, v37, s33
	v_and_or_b32 v35, v36, s96, v35
	v_bfe_u32 v36, v39, 16, 1
	v_add3_u32 v36, v39, v36, s33
	v_bfe_u32 v37, v38, 16, 1
	v_lshrrev_b32_e32 v36, 16, v36
	v_add3_u32 v37, v38, v37, s33
	v_and_or_b32 v36, v37, s96, v36
	v_bfe_u32 v37, v133, 16, 1
	v_add3_u32 v37, v133, v37, s33
	v_bfe_u32 v38, v129, 16, 1
	v_lshrrev_b32_e32 v37, 16, v37
	v_add3_u32 v38, v129, v38, s33
	v_and_or_b32 v37, v38, s96, v37
	v_bfe_u32 v38, v130, 16, 1
	v_add3_u32 v38, v130, v38, s33
	v_bfe_u32 v39, v127, 16, 1
	v_lshrrev_b32_e32 v38, 16, v38
	v_add3_u32 v39, v127, v39, s33
	v_and_or_b32 v38, v39, s96, v38
	v_bfe_u32 v39, v134, 16, 1
	v_add3_u32 v39, v134, v39, s33
	v_bfe_u32 v127, v131, 16, 1
	v_lshrrev_b32_e32 v39, 16, v39
	v_add3_u32 v127, v131, v127, s33
	v_and_or_b32 v39, v127, s96, v39
	v_bfe_u32 v127, v40, 16, 1
	v_add3_u32 v40, v40, v127, s33
	v_bfe_u32 v127, v126, 16, 1
	v_lshrrev_b32_e32 v40, 16, v40
	v_add3_u32 v126, v126, v127, s33
	v_and_or_b32 v40, v126, s96, v40
	v_bfe_u32 v126, v128, 16, 1
	v_add3_u32 v126, v128, v126, s33
	v_bfe_u32 v127, v41, 16, 1
	v_lshrrev_b32_e32 v126, 16, v126
	v_add3_u32 v41, v41, v127, s33
	v_and_or_b32 v41, v41, s96, v126
	v_bfe_u32 v126, v44, 16, 1
	v_add3_u32 v44, v44, v126, s33
	v_bfe_u32 v126, v42, 16, 1
	v_lshrrev_b32_e32 v44, 16, v44
	v_add3_u32 v42, v42, v126, s33
	v_and_or_b32 v42, v42, s96, v44
	v_bfe_u32 v44, v45, 16, 1
	v_add3_u32 v44, v45, v44, s33
	v_bfe_u32 v45, v43, 16, 1
	v_lshrrev_b32_e32 v44, 16, v44
	v_add3_u32 v43, v43, v45, s33
	v_and_or_b32 v43, v43, s96, v44
	v_bfe_u32 v44, v46, 16, 1
	v_add3_u32 v44, v46, v44, s33
	v_bfe_u32 v45, v51, 16, 1
	v_lshrrev_b32_e32 v44, 16, v44
	v_add3_u32 v45, v51, v45, s33
	v_and_or_b32 v44, v45, s96, v44
	v_bfe_u32 v45, v56, 16, 1
	v_add3_u32 v45, v56, v45, s33
	v_bfe_u32 v46, v52, 16, 1
	v_lshrrev_b32_e32 v45, 16, v45
	v_add3_u32 v46, v52, v46, s33
	v_and_or_b32 v45, v46, s96, v45
	v_bfe_u32 v46, v55, 16, 1
	v_add3_u32 v46, v55, v46, s33
	v_bfe_u32 v51, v47, 16, 1
	v_lshrrev_b32_e32 v46, 16, v46
	v_add3_u32 v47, v47, v51, s33
	v_and_or_b32 v46, v47, s96, v46
	v_bfe_u32 v47, v57, 16, 1
	v_add3_u32 v47, v57, v47, s33
	v_bfe_u32 v51, v53, 16, 1
	v_lshrrev_b32_e32 v47, 16, v47
	v_add3_u32 v51, v53, v51, s33
; __device__ __forceinline__ unsigned pk2(float lo, float hi) { return f2bf(lo) | (f2bf(hi) << 16); }
; __device__ __forceinline__ void phase_prep(const Args& A, const Ctx& C0, int l) {
;     ...
;     { const int fr = C.lane & 15, fq = C.lane >> 4;
; #pragma unroll
;       for (int mat = 0; mat < 2; ++mat) { const float* W = A.in[mat ? I_AUP : I_WUP] + (size_t)l * 64 * 512 + head * 64 + fr;
; #pragma unroll
;           for (int ct = 0; ct < 4; ++ct)
; #pragma unroll
;               for (int ks = 0; ks < 2; ++ks) { const float* p = W + (size_t)(ks * 32 + 8 * fq) * 512 + ct * 16;
;                   union { bf16x8 v; unsigned w[4]; } f;
; #pragma unroll
;                   for (int e = 0; e < 4; ++e) f.w[e] = pk2(p[(2 * e) * 512], p[(2 * e + 1) * 512]);
;                   wfr[mat][ct][ks] = f.v; } } }
	v_and_or_b32 v47, v51, s96, v47
	v_bfe_u32 v51, v48, 16, 1
	v_add3_u32 v48, v48, v51, s33
	v_bfe_u32 v51, v49, 16, 1
	v_lshrrev_b32_e32 v48, 16, v48
	v_add3_u32 v49, v49, v51, s33
	v_and_or_b32 v48, v49, s96, v48
	v_bfe_u32 v49, v54, 16, 1
	v_add3_u32 v49, v54, v49, s33
	v_bfe_u32 v51, v50, 16, 1
	v_lshrrev_b32_e32 v49, 16, v49
	v_add3_u32 v50, v50, v51, s33
	v_and_or_b32 v49, v50, s96, v49
	v_bfe_u32 v50, v124, 16, 1
	v_add3_u32 v50, v124, v50, s33
	v_bfe_u32 v51, v112, 16, 1
	v_lshrrev_b32_e32 v50, 16, v50
	v_add3_u32 v51, v112, v51, s33
	v_and_or_b32 v50, v51, s96, v50
	v_bfe_u32 v51, v141, 16, 1
	v_add3_u32 v51, v141, v51, s33
	v_bfe_u32 v52, v138, 16, 1
	v_lshrrev_b32_e32 v51, 16, v51
	v_add3_u32 v52, v138, v52, s33
	v_and_or_b32 v51, v52, s96, v51
	v_bfe_u32 v52, v140, 16, 1
	v_add3_u32 v52, v140, v52, s33
	v_bfe_u32 v53, v139, 16, 1
	v_lshrrev_b32_e32 v52, 16, v52
	v_add3_u32 v53, v139, v53, s33
	v_and_or_b32 v52, v53, s96, v52
	v_bfe_u32 v53, v136, 16, 1
	v_add3_u32 v53, v136, v53, s33
	v_bfe_u32 v54, v148, 16, 1
	v_lshrrev_b32_e32 v53, 16, v53
	v_add3_u32 v54, v148, v54, s33
	v_and_or_b32 v53, v54, s96, v53
	v_bfe_u32 v54, v145, 16, 1
	v_add3_u32 v54, v145, v54, s33
	v_bfe_u32 v55, v146, 16, 1
	v_lshrrev_b32_e32 v54, 16, v54
	v_add3_u32 v55, v146, v55, s33
	v_and_or_b32 v54, v55, s96, v54
	v_bfe_u32 v55, v137, 16, 1
	v_add3_u32 v55, v137, v55, s33
	v_bfe_u32 v56, v149, 16, 1
	v_lshrrev_b32_e32 v55, 16, v55
	v_add3_u32 v56, v149, v56, s33
	v_and_or_b32 v55, v56, s96, v55
	v_bfe_u32 v56, v135, 16, 1
	v_add3_u32 v56, v135, v56, s33
	v_bfe_u32 v57, v132, 16, 1
	v_lshrrev_b32_e32 v56, 16, v56
	v_add3_u32 v57, v132, v57, s33
	v_and_or_b32 v56, v57, s96, v56
	v_bfe_u32 v57, v144, 16, 1
	v_add3_u32 v57, v144, v57, s33
	v_bfe_u32 v112, v147, 16, 1
	v_lshrrev_b32_e32 v57, 16, v57
	v_add3_u32 v112, v147, v112, s33
	v_and_or_b32 v57, v112, s96, v57
	v_bfe_u32 v112, v59, 16, 1
	v_add3_u32 v59, v59, v112, s33
	v_bfe_u32 v112, v58, 16, 1
	v_lshrrev_b32_e32 v59, 16, v59
	v_add3_u32 v58, v58, v112, s33
	v_and_or_b32 v58, v58, s96, v59
	v_bfe_u32 v59, v61, 16, 1
	v_add3_u32 v59, v61, v59, s33
	v_bfe_u32 v61, v60, 16, 1
	v_lshrrev_b32_e32 v59, 16, v59
	v_add3_u32 v60, v60, v61, s33
	v_and_or_b32 v59, v60, s96, v59
	v_bfe_u32 v60, v63, 16, 1
	v_add3_u32 v60, v63, v60, s33
	v_bfe_u32 v61, v62, 16, 1
	v_lshrrev_b32_e32 v60, 16, v60
	v_add3_u32 v61, v62, v61, s33
	v_and_or_b32 v60, v61, s96, v60
	v_bfe_u32 v61, v125, 16, 1
	v_add3_u32 v61, v125, v61, s33
	v_bfe_u32 v62, v115, 16, 1
	v_lshrrev_b32_e32 v61, 16, v61
	v_add3_u32 v62, v115, v62, s33
	v_and_or_b32 v61, v62, s96, v61
	v_bfe_u32 v62, v113, 16, 1
	v_add3_u32 v62, v113, v62, s33
	v_bfe_u32 v63, v111, 16, 1
	v_lshrrev_b32_e32 v62, 16, v62
	v_add3_u32 v63, v111, v63, s33
	v_and_or_b32 v62, v63, s96, v62
	v_bfe_u32 v63, v109, 16, 1
	v_add3_u32 v63, v109, v63, s33
	v_bfe_u32 v109, v114, 16, 1
	v_lshrrev_b32_e32 v63, 16, v63
	v_add3_u32 v109, v114, v109, s33
	v_and_or_b32 v63, v109, s96, v63
	v_bfe_u32 v109, v65, 16, 1
	v_add3_u32 v65, v65, v109, s33
	v_bfe_u32 v109, v64, 16, 1
	v_lshrrev_b32_e32 v65, 16, v65
	v_add3_u32 v64, v64, v109, s33
	v_and_or_b32 v64, v64, s96, v65
	v_bfe_u32 v65, v108, 16, 1
	v_add3_u32 v65, v108, v65, s33
	v_bfe_u32 v108, v110, 16, 1
	v_lshrrev_b32_e32 v65, 16, v65
	v_add3_u32 v108, v110, v108, s33
	v_and_or_b32 v65, v108, s96, v65
	v_bfe_u32 v108, v67, 16, 1
	v_add3_u32 v67, v67, v108, s33
	v_bfe_u32 v108, v66, 16, 1
	v_lshrrev_b32_e32 v67, 16, v67
	v_add3_u32 v66, v66, v108, s33
	v_and_or_b32 v66, v66, s96, v67
	v_bfe_u32 v67, v69, 16, 1
	v_add3_u32 v67, v69, v67, s33
	v_bfe_u32 v69, v68, 16, 1
	v_lshrrev_b32_e32 v67, 16, v67
	v_add3_u32 v68, v68, v69, s33
	v_and_or_b32 v67, v68, s96, v67
	v_bfe_u32 v68, v71, 16, 1
	v_add3_u32 v68, v71, v68, s33
	v_bfe_u32 v69, v70, 16, 1
	v_lshrrev_b32_e32 v68, 16, v68
	v_add3_u32 v69, v70, v69, s33
	v_and_or_b32 v68, v69, s96, v68
	v_bfe_u32 v69, v106, 16, 1
	v_add3_u32 v69, v106, v69, s33
	v_bfe_u32 v70, v103, 16, 1
	v_lshrrev_b32_e32 v69, 16, v69
	v_add3_u32 v70, v103, v70, s33
	v_and_or_b32 v69, v70, s96, v69
	v_bfe_u32 v70, v104, 16, 1
	v_add3_u32 v70, v104, v70, s33
	v_bfe_u32 v71, v96, 16, 1
	v_lshrrev_b32_e32 v70, 16, v70
	v_add3_u32 v71, v96, v71, s33
	v_and_or_b32 v70, v71, s96, v70
	v_bfe_u32 v71, v107, 16, 1
	v_add3_u32 v71, v107, v71, s33
	v_bfe_u32 v96, v105, 16, 1
	v_lshrrev_b32_e32 v71, 16, v71
	v_add3_u32 v96, v105, v96, s33
	v_and_or_b32 v71, v96, s96, v71
	v_bfe_u32 v96, v72, 16, 1
	v_add3_u32 v72, v72, v96, s33
	v_bfe_u32 v96, v93, 16, 1
	v_lshrrev_b32_e32 v72, 16, v72
	v_add3_u32 v93, v93, v96, s33
	v_and_or_b32 v72, v93, s96, v72
	v_bfe_u32 v93, v102, 16, 1
	v_add3_u32 v93, v102, v93, s33
	v_bfe_u32 v96, v73, 16, 1
	v_lshrrev_b32_e32 v93, 16, v93
	v_add3_u32 v73, v73, v96, s33
	v_and_or_b32 v73, v73, s96, v93
	v_bfe_u32 v93, v76, 16, 1
	v_add3_u32 v76, v76, v93, s33
	v_bfe_u32 v93, v74, 16, 1
	v_lshrrev_b32_e32 v76, 16, v76
	v_add3_u32 v74, v74, v93, s33
	v_and_or_b32 v74, v74, s96, v76
	v_bfe_u32 v76, v77, 16, 1
	v_add3_u32 v76, v77, v76, s33
	v_bfe_u32 v77, v75, 16, 1
	v_lshrrev_b32_e32 v76, 16, v76
	v_add3_u32 v75, v75, v77, s33
	v_and_or_b32 v75, v75, s96, v76
	v_bfe_u32 v76, v78, 16, 1
	v_add3_u32 v76, v78, v76, s33
	v_bfe_u32 v77, v86, 16, 1
	v_lshrrev_b32_e32 v76, 16, v76
; #define LAS __attribute__((address_space(3)))
; __device__ __forceinline__ void phase_prep(const Args& A, const Ctx& C0, int l) {
;     ...
;     LAS bf16* lob = (LAS bf16*)(C.lds + 9 * DSH * 4);
;     LAS float* outw = (LAS float*)(C.lds + 9 * DSH * 4 + 16 * 136 * 2);
;     LAS float* outa = outw + 8 * 512;
;     const float w0 = A.in[I_W0][l * 512 + c], a0 = A.in[I_A0][l * 512 + c], kkc = A.in[I_KK][l * 512 + c], kac = A.in[I_KA][l * 512 + c], rkc = A.in[I_RK][l * 512 + c];
;     const float* mul = A.in[I_MU] + (size_t)l * DSH;
;     const float mu_r = mul[c], mu_k = mul[512 + c], mu_v = mul[1024 + c];
;     v4u px[4];
;     ...
;     if (C.bid < M / 8) PREP_FETCH(C.bid);
;     ...
;         for (int k = 0; k < 2; ++k) { const int idx = C.tid + 512 * k, tt = idx >> 7, j = idx & 127, i = 1536 + j;
;             const float cur = raw[(tt + 1) * DSH + i], prev = raw[tt * DSH + i]; const float xs = cur + (prev - cur) * mul[i];
	v_add3_u32 v77, v86, v77, s33
	v_and_or_b32 v76, v77, s96, v76
	v_bfe_u32 v77, v91, 16, 1
	v_add3_u32 v77, v91, v77, s33
	v_bfe_u32 v78, v87, 16, 1
	v_lshrrev_b32_e32 v77, 16, v77
	v_add3_u32 v78, v87, v78, s33
	v_and_or_b32 v77, v78, s96, v77
	v_bfe_u32 v78, v90, 16, 1
	v_add3_u32 v78, v90, v78, s33
	v_bfe_u32 v86, v79, 16, 1
	v_lshrrev_b32_e32 v78, 16, v78
	v_add3_u32 v79, v79, v86, s33
	v_and_or_b32 v78, v79, s96, v78
	v_bfe_u32 v79, v92, 16, 1
	v_add3_u32 v79, v92, v79, s33
	v_bfe_u32 v86, v88, 16, 1
	v_lshrrev_b32_e32 v79, 16, v79
	v_add3_u32 v86, v88, v86, s33
	v_and_or_b32 v79, v86, s96, v79
	v_bfe_u32 v86, v80, 16, 1
	v_add3_u32 v80, v80, v86, s33
	v_bfe_u32 v86, v81, 16, 1
	v_lshrrev_b32_e32 v80, 16, v80
	v_add3_u32 v81, v81, v86, s33
	v_and_or_b32 v80, v81, s96, v80
	v_bfe_u32 v81, v89, 16, 1
	s_mov_b32 s11, 0x4ec4ec4f
	v_add3_u32 v81, v89, v81, s33
	v_bfe_u32 v86, v85, 16, 1
	s_ashr_i32 s1, s9, 6
	v_mul_hi_i32 v92, v84, s11
	v_lshrrev_b32_e32 v81, 16, v81
	v_add3_u32 v85, v85, v86, s33
	s_add_u32 s9, s42, 0x7984000
	s_mul_i32 s2, s1, 0x180
	v_lshrrev_b32_e32 v93, 31, v92
	v_ashrrev_i32_e32 v92, 6, v92
	v_and_or_b32 v81, v85, s96, v81
	s_addc_u32 s15, s43, 0
	v_and_b32_e32 v85, 0x7f, v94
	s_ashr_i32 s3, s2, 31
	v_add_u32_e32 v126, v92, v93
	v_add_u32_e32 v93, 0x600, v94
	v_lshlrev_b32_e32 v88, 2, v85
	s_lshl_b64 s[2:3], s[2:3], 2
	v_mul_hi_i32 v96, v93, s11
	v_or_b32_e32 v86, 0x1800, v88
	v_mov_b32_e32 v87, v1
	s_movk_i32 s13, 0x110
	s_add_u32 s2, s42, s2
	v_lshrrev_b32_e32 v112, 31, v96
	v_ashrrev_i32_e32 v96, 6, v96
	v_lshl_add_u64 v[102:103], s[38:39], 0, v[86:87]
	v_mad_u32_u24 v86, v83, s13, 0
	v_lshlrev_b32_e32 v89, 13, v82
	s_addc_u32 s3, s43, s3
	v_lshlrev_b32_e32 v82, 2, v166
	v_mov_b32_e32 v83, v1
	s_movk_i32 s12, 0xd0
	v_add_u32_e32 v127, v96, v112
	v_lshl_add_u64 v[82:83], s[2:3], 0, v[82:83]
	s_mov_b64 s[2:3], 0x256d7900
	v_mul_lo_u32 v96, v127, s12
	s_lshl_b32 s0, s0, 2
	v_lshl_add_u64 v[104:105], v[82:83], 0, s[2:3]
	s_movk_i32 s2, 0x680
	s_movk_i32 s14, 0x19f
	s_movk_i32 s3, 0x1a00
	v_sub_u32_e32 v93, v93, v96
	v_add_u32_e32 v96, 0x6cf, v94
	s_add_i32 s0, s0, 0
	v_cmp_gt_i32_e64 s[44:45], s2, v94
	s_movk_i32 s2, 0x74f
	v_cmp_gt_u32_e64 s[68:69], s14, v96
	v_mul_lo_u32 v96, v127, s3
	v_add3_u32 v130, s0, v89, v0
	s_add_i32 s0, s0, 0x13b00
	v_cmp_lt_i32_e64 s[46:47], s2, v94
	s_movk_i32 s2, 0x750
	v_add_u32_e32 v115, 0, v96
	v_ashrrev_i32_e32 v96, 7, v94
	v_add3_u32 v0, s0, v89, v0
	v_max_i32_e32 v89, 0x480, v94
	v_mul_hi_i32 v82, v94, s11
	v_cmp_gt_i32_e64 s[48:49], s2, v94
	v_mul_hi_i32 v90, v97, s11
	s_movk_i32 s2, 0x54f
	v_mul_lo_u32 v114, v96, s3
	v_mul_lo_u32 v139, v96, s13
	v_ashrrev_i32_e32 v96, 7, v97
	v_sub_u32_e32 v89, v89, v94
	v_lshrrev_b32_e32 v83, 31, v82
	v_ashrrev_i32_e32 v82, 6, v82
	v_lshrrev_b32_e32 v91, 31, v90
	v_ashrrev_i32_e32 v90, 6, v90
	v_cmp_lt_i32_e64 s[52:53], s2, v94
	s_movk_i32 s2, 0x550
	v_add3_u32 v128, 0, v114, v88
	v_mul_lo_u32 v114, v96, s3
	v_add_u32_e32 v89, 0x1ff, v89
	v_add_u32_e32 v124, v82, v83
	v_add_u32_e32 v125, v90, v91
	v_cmp_gt_i32_e64 s[54:55], s2, v94
	v_mul_lo_u32 v92, v126, s12
	s_movk_i32 s2, 0x34f
	v_add3_u32 v129, 0, v114, v88
	v_mul_lo_u32 v88, v96, s13
	v_lshrrev_b32_e32 v96, 9, v89
	v_mul_lo_u32 v82, v124, s12
	v_add_u32_e32 v83, 0xcf, v94
	v_mul_lo_u32 v90, v125, s12
	v_add_u32_e32 v91, 0x2cf, v94
	v_sub_u32_e32 v84, v84, v92
	v_cmp_lt_i32_e64 s[58:59], s2, v94
	s_movk_i32 s2, 0x350
	v_add_u32_e32 v92, 0x4cf, v94
	v_add_u32_e32 v133, 1, v96
	s_movk_i32 s0, 0x1ff
	v_sub_u32_e32 v82, v94, v82
	v_cmp_gt_u32_e64 s[50:51], s14, v83
	v_mul_lo_u32 v83, v124, s3
	v_sub_u32_e32 v90, v97, v90
	v_cmp_gt_u32_e64 s[56:57], s14, v91
	v_mul_lo_u32 v91, v125, s3
	v_cmp_gt_i32_e64 s[60:61], s2, v94
	v_cmp_gt_u32_e64 s[62:63], s14, v92
	v_mul_lo_u32 v92, v126, s3
	s_movk_i32 s2, 0x14f
	v_cmp_lt_u32_e64 s[70:71], s0, v89
	v_and_b32_e32 v132, 0xfffffe, v133
	s_lshl_b32 s0, s8, 6
	v_cmp_gt_u32_e64 s[38:39], 64, v85
	v_lshl_add_u32 v85, v85, 1, 0
	v_and_b32_e32 v87, 48, v94
	v_lshlrev_b32_e32 v106, 3, v82
	v_add_u32_e32 v83, 0, v83
	v_lshlrev_b32_e32 v82, 5, v82
	v_lshlrev_b32_e32 v108, 3, v90
	v_add_u32_e32 v91, 0, v91
	v_lshlrev_b32_e32 v90, 5, v90
	v_lshlrev_b32_e32 v110, 3, v84
	v_add_u32_e32 v92, 0, v92
	v_lshlrev_b32_e32 v84, 5, v84
	v_cmp_lt_i32_e64 s[64:65], s2, v94
	s_movk_i32 s2, 0x150
	v_lshlrev_b32_e32 v112, 3, v93
	v_lshlrev_b32_e32 v93, 5, v93
	v_cmp_ne_u32_e64 s[26:27], v133, v132
	v_lshlrev_b32_e32 v133, 2, v94
	s_add_i32 s19, s1, s0
	v_readlane_b32 s0, v254, 60
	v_cmp_gt_u32_e64 s[40:41], 32, v166
	v_cmp_eq_u32_e64 s[42:43], 0, v166
	v_ashrrev_i32_e32 v107, 31, v106
	v_ashrrev_i32_e32 v109, 31, v108
	v_ashrrev_i32_e32 v111, 31, v110
	v_cmp_gt_i32_e64 s[66:67], s2, v94
	v_ashrrev_i32_e32 v113, 31, v112
	v_add_u32_e32 v131, 0xfb00, v130
	v_lshl_add_u32 v114, v132, 9, v94
	v_mov_b32_e32 v96, v94
	s_lshl_b32 s12, s10, 6
	s_lshl_b32 s18, s8, 3
	s_lshl_b32 s14, s10, 3
	v_add_u32_e32 v134, s0, v133
	v_add_u32_e32 v135, v83, v82
	v_add_u32_e32 v136, v91, v90
	v_add_u32_e32 v137, v92, v84
	v_add_u32_e32 v138, v115, v93
	v_add_u32_e32 v139, v85, v139
	v_add_u32_e32 v140, v85, v88
	v_add_u32_e32 v141, v86, v87
	s_mov_b32 s16, s8
	global_load_dword v168, v[102:103], off
	s_waitcnt vmcnt(0)
	s_branch .LBB0_46

; #define LAS __attribute__((address_space(3)))
; __device__ __forceinline__ float bflo(unsigned w) { return __uint_as_float(w << 16); }
; __device__ __forceinline__ float bfhi(unsigned w) { return __uint_as_float(w & 0xffff0000u); }
; __device__ __forceinline__ void phase_prep(const Args& A, const Ctx& C0, int l) {
;     ...
;     if (C.bid < M / 8) PREP_FETCH(C.bid);
;     for (int tile = C.bid; tile < M / 8; tile += C.G) {
;         const int row0 = tile * 8;
;         bool seq_start; const float* shiftp = nullptr;
;         if (row0 < MP) seq_start = (row0 % SEQ) == 0; else { const int rs = row0 - MP; seq_start = (rs % DECS) == 0; shiftp = A.in[I_SSHIFT] + (size_t)(l * DECB + rs / DECS) * DSH; }
; #pragma unroll
;         for (int it = 0; it < 4; ++it) { const int idx = C.tid + 512 * it; const int rr = idx / 208, v = idx % 208;
;             if (idx < 9 * 208) { const v4u x = px[it];
;                 f32x4 f0 = (f32x4){bflo(x.x), bfhi(x.x), bflo(x.y), bfhi(x.y)}, f1 = (f32x4){bflo(x.z), bfhi(x.z), bflo(x.w), bfhi(x.w)};
;                 if (rr == 0 && seq_start && shiftp) { f0 = *(const f32x4*)(shiftp + v * 8); f1 = *(const f32x4*)(shiftp + v * 8 + 4); }
;                 *(LAS f32x4*)(raw + rr * DSH + v * 8) = f0; *(LAS f32x4*)(raw + rr * DSH + v * 8 + 4) = f1; } }
;         if (tile + C.G < M / 8) PREP_FETCH(tile + C.G);
.LBB0_54:
	s_and_b64 s[2:3], s[50:51], s[78:79]
	s_waitcnt lgkmcnt(0)
	v_lshlrev_b32_e32 v82, 16, v2
	v_and_b32_e32 v83, 0xffff0000, v2
	v_lshlrev_b32_e32 v84, 16, v3
	v_and_b32_e32 v85, 0xffff0000, v3
	v_lshlrev_b32_e32 v86, 16, v4
	v_and_b32_e32 v87, 0xffff0000, v4
	v_lshlrev_b32_e32 v88, 16, v5
	v_and_b32_e32 v89, 0xffff0000, v5
	s_and_b64 s[74:75], s[2:3], vcc
	s_and_saveexec_b64 s[2:3], s[74:75]
	s_cbranch_execz .LBB0_56
	v_lshl_add_u64 v[82:83], v[106:107], 2, s[0:1]
	global_load_dwordx4 v[86:89], v[82:83], off offset:16
	s_nop 0
	global_load_dwordx4 v[82:85], v[82:83], off
	s_waitcnt vmcnt(0)
.LBB0_56:
	s_or_b64 exec, exec, s[2:3]
	s_waitcnt vmcnt(48)
	ds_write_b128 v135, v[82:85]
	ds_write_b128 v135, v[86:89] offset:16
	s_or_b64 exec, exec, s[30:31]
	s_and_saveexec_b64 s[30:31], s[54:55]
	s_cbranch_execz .LBB0_52
.LBB0_57:
	s_and_b64 s[2:3], s[56:57], s[78:79]
	s_waitcnt lgkmcnt(0)
	v_lshlrev_b32_e32 v82, 16, v6
	v_and_b32_e32 v83, 0xffff0000, v6
	v_lshlrev_b32_e32 v84, 16, v7
	v_and_b32_e32 v85, 0xffff0000, v7
	v_lshlrev_b32_e32 v86, 16, v8
	v_and_b32_e32 v87, 0xffff0000, v8
	v_lshlrev_b32_e32 v88, 16, v9
	v_and_b32_e32 v89, 0xffff0000, v9
	s_and_b64 s[74:75], s[2:3], vcc
	s_and_saveexec_b64 s[2:3], s[74:75]
	s_cbranch_execz .LBB0_59
	v_lshl_add_u64 v[82:83], v[108:109], 2, s[0:1]
	global_load_dwordx4 v[86:89], v[82:83], off offset:16
	s_nop 0
	global_load_dwordx4 v[82:85], v[82:83], off
	s_waitcnt vmcnt(0)
.LBB0_59:
	s_or_b64 exec, exec, s[2:3]
	s_waitcnt vmcnt(48)
	ds_write_b128 v136, v[82:85]
	ds_write_b128 v136, v[86:89] offset:16
	s_or_b64 exec, exec, s[30:31]
	s_and_saveexec_b64 s[30:31], s[60:61]
	s_cbranch_execz .LBB0_53
.LBB0_60:
	s_and_b64 s[2:3], s[62:63], s[78:79]
	s_waitcnt lgkmcnt(0)
	v_lshlrev_b32_e32 v82, 16, v10
	v_and_b32_e32 v83, 0xffff0000, v10
	v_lshlrev_b32_e32 v84, 16, v11
	v_and_b32_e32 v85, 0xffff0000, v11
	v_lshlrev_b32_e32 v86, 16, v12
	v_and_b32_e32 v87, 0xffff0000, v12
	v_lshlrev_b32_e32 v88, 16, v13
	v_and_b32_e32 v89, 0xffff0000, v13
	s_and_b64 s[74:75], s[2:3], vcc
	s_and_saveexec_b64 s[2:3], s[74:75]
	s_cbranch_execz .LBB0_62
	v_lshl_add_u64 v[82:83], v[110:111], 2, s[0:1]
	global_load_dwordx4 v[86:89], v[82:83], off offset:16
	s_nop 0
	global_load_dwordx4 v[82:85], v[82:83], off
	s_waitcnt vmcnt(0)
.LBB0_62:
	s_or_b64 exec, exec, s[2:3]
	s_waitcnt vmcnt(48)
	ds_write_b128 v137, v[82:85]
	ds_write_b128 v137, v[86:89] offset:16
	s_or_b64 exec, exec, s[30:31]
	s_and_saveexec_b64 s[30:31], s[66:67]
	s_cbranch_execz .LBB0_66
.LBB0_63:
	s_and_b64 s[2:3], s[68:69], s[78:79]
	s_waitcnt lgkmcnt(0)
	v_lshlrev_b32_e32 v82, 16, v14
	v_and_b32_e32 v83, 0xffff0000, v14
	v_lshlrev_b32_e32 v84, 16, v15
	v_and_b32_e32 v85, 0xffff0000, v15
	v_lshlrev_b32_e32 v86, 16, v16
	v_and_b32_e32 v87, 0xffff0000, v16
	v_lshlrev_b32_e32 v88, 16, v17
	v_and_b32_e32 v89, 0xffff0000, v17
	s_and_b64 s[74:75], s[2:3], vcc
	s_and_saveexec_b64 s[2:3], s[74:75]
	s_cbranch_execz .LBB0_65
	v_lshl_add_u64 v[82:83], v[112:113], 2, s[0:1]
	global_load_dwordx4 v[86:89], v[82:83], off offset:16
	s_nop 0
	global_load_dwordx4 v[82:85], v[82:83], off
	s_waitcnt vmcnt(0)
.LBB0_65:
	s_or_b64 exec, exec, s[2:3]
	s_waitcnt vmcnt(48)
	ds_write_b128 v138, v[82:85]
	ds_write_b128 v138, v[86:89] offset:16
.LBB0_66:
	s_or_b64 exec, exec, s[30:31]
	s_add_i32 s16, s16, s10
	s_cmpk_gt_i32 s16, 0x101f
	s_cselect_b64 s[78:79], -1, 0
	s_and_b64 vcc, exec, s[78:79]
	s_cbranch_vccnz .LBB0_76
	s_lshl_b32 s30, s16, 3
	s_cmpk_lt_i32 s16, 0x1000
	s_cselect_b32 s0, 0x3ff, 3
	s_and_b32 s0, s0, s16
	s_cmp_eq_u32 s0, 0
	s_cselect_b64 s[0:1], -1, 0
	s_and_b64 s[2:3], s[50:51], s[0:1]
	s_add_i32 s30, s30, -1
	s_nor_b64 s[74:75], s[46:47], s[2:3]
	s_waitcnt lgkmcnt(0)
	v_mov_b32_e32 v10, 0
	v_mov_b32_e32 v2, 0
	v_mov_b32_e32 v3, 0
	v_mov_b32_e32 v4, 0
	v_mov_b32_e32 v5, 0
	s_and_saveexec_b64 s[2:3], s[74:75]
	s_cbranch_execz .LBB0_69
	v_add_u32_e32 v4, s30, v124
	v_mov_b64_e32 v[2:3], s[76:77]
	s_movk_i32 s11, 0x2b00
	v_mad_i64_i32 v[2:3], s[74:75], v4, s11, v[2:3]
	v_lshl_add_u64 v[2:3], v[106:107], 1, v[2:3]
	v_add_co_u32_e32 v2, vcc, 0x1000, v2
	s_nop 1
	v_addc_co_u32_e32 v3, vcc, 0, v3, vcc
	global_load_dwordx4 v[2:5], v[2:3], off offset:2560
.LBB0_69:
	s_or_b64 exec, exec, s[2:3]
	s_and_b64 s[2:3], s[56:57], s[0:1]
	s_nor_b64 s[74:75], s[52:53], s[2:3]
	v_mov_b32_e32 v6, 0
	v_mov_b32_e32 v7, 0
	v_mov_b32_e32 v8, 0
	v_mov_b32_e32 v9, 0
	s_and_saveexec_b64 s[2:3], s[74:75]
	s_cbranch_execz .LBB0_71
	v_add_u32_e32 v8, s30, v125
	v_mov_b64_e32 v[6:7], s[76:77]
	s_movk_i32 s11, 0x2b00
	v_mad_i64_i32 v[6:7], s[74:75], v8, s11, v[6:7]
	v_lshl_add_u64 v[6:7], v[108:109], 1, v[6:7]
	v_add_co_u32_e32 v6, vcc, 0x1000, v6
	s_nop 1
	v_addc_co_u32_e32 v7, vcc, 0, v7, vcc
	global_load_dwordx4 v[6:9], v[6:7], off offset:2560
.LBB0_71:
	s_or_b64 exec, exec, s[2:3]
	s_and_b64 s[2:3], s[62:63], s[0:1]
	s_nor_b64 s[74:75], s[58:59], s[2:3]
	v_mov_b32_e32 v11, 0
	v_mov_b32_e32 v12, 0
	v_mov_b32_e32 v13, 0
	s_and_saveexec_b64 s[2:3], s[74:75]
	s_cbranch_execz .LBB0_73
	v_add_u32_e32 v12, s30, v126
	v_mov_b64_e32 v[10:11], s[76:77]
	s_movk_i32 s11, 0x2b00
	v_mad_i64_i32 v[10:11], s[74:75], v12, s11, v[10:11]
	v_lshl_add_u64 v[10:11], v[110:111], 1, v[10:11]
	v_add_co_u32_e32 v10, vcc, 0x1000, v10
	s_nop 1
	v_addc_co_u32_e32 v11, vcc, 0, v11, vcc
	global_load_dwordx4 v[10:13], v[10:11], off offset:2560
.LBB0_73:
	s_or_b64 exec, exec, s[2:3]
	s_and_b64 s[0:1], s[68:69], s[0:1]
	s_nor_b64 s[2:3], s[64:65], s[0:1]
	v_mov_b32_e32 v17, 0
	v_mov_b32_e32 v16, 0
	v_mov_b32_e32 v15, 0
	v_mov_b32_e32 v14, 0
	s_and_saveexec_b64 s[0:1], s[2:3]
	s_cbranch_execz .LBB0_75
	v_add_u32_e32 v16, s30, v127
	v_mov_b64_e32 v[14:15], s[76:77]
	s_movk_i32 s2, 0x2b00
	v_mad_i64_i32 v[14:15], s[2:3], v16, s2, v[14:15]
	v_lshl_add_u64 v[14:15], v[112:113], 1, v[14:15]
	v_add_co_u32_e32 v14, vcc, 0x1000, v14
	s_nop 1
	v_addc_co_u32_e32 v15, vcc, 0, v15, vcc
	global_load_dwordx4 v[14:17], v[14:15], off offset:2560

; __device__ __forceinline__ unsigned f2bf(float f) { unsigned u = __builtin_bit_cast(unsigned, f); return (u + 0x7fffu + ((u >> 16) & 1u)) >> 16; }
; __device__ __forceinline__ void phase_prep(const Args& A, const Ctx& C0, int l) {
;     ...
;         for (int k = 0; k < 2; ++k) { const int idx = C.tid + 512 * k, tt = idx >> 7, j = idx & 127, i = 1536 + j;
;             const float cur = raw[(tt + 1) * DSH + i], prev = raw[tt * DSH + i]; const float xs = cur + (prev - cur) * mul[i];
;             float o = xs; if (j < 64) { const float e = __expf(2.f * xs); o = 1.f - 2.f / (e + 1.f); }
;             lob[tt * 136 + j] = (bf16)f2bf(o); }
.LBB0_76:
	s_waitcnt lgkmcnt(0)
	s_barrier
	ds_read2st64_b32 v[82:83], v128 offset0:24 offset1:50
	s_waitcnt lgkmcnt(0)
	v_sub_f32_e32 v82, v82, v83
	v_fmac_f32_e32 v83, v168, v82
	s_and_saveexec_b64 s[0:1], s[38:39]
	s_cbranch_execz .LBB0_78
	v_add_f32_e32 v82, v83, v83
	v_mul_f32_e32 v82, 0x3fb8aa3b, v82
	v_exp_f32_e32 v82, v82
	s_nop 0
	v_add_f32_e32 v82, 1.0, v82
	v_div_scale_f32 v83, s[2:3], v82, v82, 2.0
	v_rcp_f32_e32 v85, v83
	v_div_scale_f32 v86, vcc, 2.0, v82, 2.0
	v_fma_f32 v87, -v83, v85, 1.0
	v_fmac_f32_e32 v85, v87, v85
	v_mul_f32_e32 v87, v86, v85
	v_fma_f32 v88, -v83, v87, v86
	v_fmac_f32_e32 v87, v88, v85
	v_fma_f32 v83, -v83, v87, v86
	v_div_fmas_f32 v83, v83, v85, v87
	v_div_fixup_f32 v82, v83, v82, 2.0
	v_sub_f32_e32 v83, 1.0, v82
.LBB0_78:
	s_or_b64 exec, exec, s[0:1]
	v_bfe_u32 v82, v83, 16, 1
	v_add3_u32 v82, v83, v82, s33
	ds_write_b16_d16_hi v139, v82 offset:59904
	ds_read2st64_b32 v[82:83], v129 offset0:24 offset1:50
	s_waitcnt lgkmcnt(0)
	v_sub_f32_e32 v82, v82, v83
	v_fmac_f32_e32 v83, v168, v82
	s_and_saveexec_b64 s[0:1], s[38:39]
	s_cbranch_execz .LBB0_80
	v_add_f32_e32 v82, v83, v83
	v_mul_f32_e32 v82, 0x3fb8aa3b, v82
	v_exp_f32_e32 v82, v82
	s_nop 0
	v_add_f32_e32 v82, 1.0, v82
	v_div_scale_f32 v83, s[2:3], v82, v82, 2.0
	v_rcp_f32_e32 v84, v83
	v_div_scale_f32 v85, vcc, 2.0, v82, 2.0
	v_fma_f32 v86, -v83, v84, 1.0
	v_fmac_f32_e32 v84, v86, v84
	v_mul_f32_e32 v86, v85, v84
	v_fma_f32 v87, -v83, v86, v85
	v_fmac_f32_e32 v86, v87, v84
	v_fma_f32 v83, -v83, v86, v85
	v_div_fmas_f32 v83, v83, v84, v86
	v_div_fixup_f32 v82, v83, v82, 2.0
	v_sub_f32_e32 v83, 1.0, v82

; #define LAS __attribute__((address_space(3)))
; __device__ __forceinline__ void phase_prep(const Args& A, const Ctx& C0, int l) {
;     ...
;         for (int tt = 0; tt < 8; ++tt) {
;             const float aw = outw[tt * 512 + c], aa = outa[tt * 512 + c];
;             const int row = row0 + tt;
;             const LAS float* cu = raw + (tt + 1) * DSH; const LAS float* pv = raw + tt * DSH;
;             const float r = cu[c] + (pv[c] - cu[c]) * mu_r, k = cu[512 + c] + (pv[512 + c] - cu[512 + c]) * mu_k, v = cu[1024 + c] + (pv[1024 + c] - cu[1024 + c]) * mu_v;
;             const float lw = w0 + aw; const float z = -lw;
;             const float sp = fmaxf(z, 0.f) + logf(1.f + expf(-fabsf(z)));
;             const float wraw = -sp - 0.5f; const float decay = expf(-expf(wraw));
;             const float ai = 1.f / (1.f + expf(-(a0 + aa)));
;             const float kkr = k * kkc; const float ss = wave_sum_l(kkr * kkr, C.lane);
;             const float kk = kkr / fmaxf(sqrtf(ss), 1e-12f);
;             const float k2 = k * (1.f + (ai - 1.f) * kac); const float b = kk * ai;
;             const float rk = wave_sum_l(r * k2 * rkc, C.lane);
;             float* s = SCN + (size_t)row * 3072 + head * 384 + C.lane;
;             __builtin_nontemporal_store(kk, s); __builtin_nontemporal_store(b, s + 64); __builtin_nontemporal_store(decay, s + 128); __builtin_nontemporal_store(k2, s + 192); __builtin_nontemporal_store(r, s + 256); __builtin_nontemporal_store(v, s + 320);
;             if (C.lane == 0) RKB[row * 8 + head] = rk;
.LBB0_98:
	v_add_u32_e32 v87, s30, v133
	v_add_u32_e32 v82, 0x13b00, v87
	v_add_u32_e32 v86, s74, v133
	ds_read_b32 v90, v87 offset:64256
	ds_read_b32 v91, v82
	ds_read2st64_b32 v[82:83], v86 offset0:16 offset1:26
	ds_read2st64_b32 v[88:89], v86 offset1:8
	ds_read2st64_b32 v[84:85], v86 offset0:34 offset1:42
	s_waitcnt lgkmcnt(0)
	v_sub_f32_e32 v88, v88, v83
	s_waitcnt lgkmcnt(0)
	v_sub_f32_e32 v82, v82, v85
	v_sub_f32_e32 v89, v89, v84
	v_fmac_f32_e32 v85, v123, v82
	v_add_f32_e32 v82, v116, v90
	v_fma_f32 v84, v122, v89, v84
	v_mul_f32_e64 v89, |v82|, s20
	v_fma_f32 v90, |v82|, s20, -v89
	v_rndne_f32_e32 v92, v89
	v_fma_f32 v90, |v82|, s21, v90
	v_sub_f32_e32 v89, v89, v92
	v_add_f32_e32 v89, v89, v90
	v_exp_f32_e32 v89, v89
	v_cvt_i32_f32_e32 v90, v92
	v_cmp_ngt_f32_e64 vcc, |v82|, s28
	v_fmac_f32_e32 v83, v121, v88
	v_max_f32_e64 v88, -v82, 0
	v_ldexp_f32 v89, v89, v90
	v_cndmask_b32_e32 v89, 0, v89, vcc
	v_cmp_nlt_f32_e64 vcc, |v82|, s29
	s_nop 1
	v_cndmask_b32_e32 v82, v251, v89, vcc
	v_add_f32_e32 v82, 1.0, v82
	v_cmp_gt_f32_e32 vcc, s35, v82
	s_nop 1
	v_cndmask_b32_e64 v89, 0, 32, vcc
	v_ldexp_f32 v82, v82, v89
	v_log_f32_e32 v82, v82
	s_nop 0
	v_mul_f32_e32 v89, 0x3f317217, v82
	v_fma_f32 v89, v82, s4, -v89
	v_fmac_f32_e32 v89, 0x3377d1cf, v82
	v_fmac_f32_e32 v89, 0x3f317217, v82
	v_cmp_lt_f32_e64 s[0:1], |v82|, s34
	s_nop 1
	v_cndmask_b32_e64 v82, v82, v89, s[0:1]
	v_cndmask_b32_e32 v89, 0, v142, vcc
	v_sub_f32_e32 v82, v82, v89
	v_add_f32_e32 v82, v88, v82
	v_sub_f32_e32 v82, -0.5, v82
	v_mul_f32_e32 v88, 0x3fb8aa3b, v82
	v_fma_f32 v89, v82, s97, -v88
	v_rndne_f32_e32 v90, v88
	v_fmac_f32_e32 v89, 0x32a5705f, v82
	v_sub_f32_e32 v88, v88, v90
	v_add_f32_e32 v88, v88, v89
	v_exp_f32_e32 v88, v88
	v_cvt_i32_f32_e32 v89, v90
	v_cmp_ngt_f32_e32 vcc, s5, v82
	v_ldexp_f32 v88, v88, v89
	s_nop 0
	v_cndmask_b32_e32 v88, 0, v88, vcc
	v_cmp_nlt_f32_e32 vcc, s6, v82
	s_nop 1
	v_cndmask_b32_e32 v82, v251, v88, vcc
	v_mul_f32_e32 v88, 0xbfb8aa3b, v82
	v_fma_f32 v89, v82, s20, -v88
	v_rndne_f32_e32 v90, v88
	v_fmac_f32_e32 v89, 0xb2a5705f, v82
	v_sub_f32_e32 v88, v88, v90
	v_add_f32_e32 v88, v88, v89
	v_exp_f32_e32 v88, v88
	v_cvt_i32_f32_e32 v89, v90
	v_cmp_nlt_f32_e32 vcc, s28, v82
	v_ldexp_f32 v88, v88, v89
	s_nop 0
	v_cndmask_b32_e32 v88, 0, v88, vcc
	v_cmp_ngt_f32_e32 vcc, s29, v82
	s_nop 1
	v_cndmask_b32_e32 v82, v251, v88, vcc
	v_add_f32_e32 v88, v117, v91
	v_mul_f32_e32 v89, 0xbfb8aa3b, v88
	v_fma_f32 v90, v88, s20, -v89
	v_rndne_f32_e32 v91, v89
	v_fmac_f32_e32 v90, 0xb2a5705f, v88
	v_sub_f32_e32 v89, v89, v91
	v_add_f32_e32 v89, v89, v90
	v_exp_f32_e32 v89, v89
	v_cvt_i32_f32_e32 v90, v91
	v_cmp_nlt_f32_e32 vcc, s28, v88
	v_ldexp_f32 v89, v89, v90
	s_nop 0
	v_cndmask_b32_e32 v89, 0, v89, vcc
	v_cmp_ngt_f32_e32 vcc, s29, v88
	s_nop 1
	v_cndmask_b32_e32 v88, v251, v89, vcc
	v_add_f32_e32 v88, 1.0, v88
	v_div_scale_f32 v89, s[0:1], v88, v88, 1.0
	v_rcp_f32_e32 v90, v89
	s_nop 0
	v_fma_f32 v91, -v89, v90, 1.0
	v_fmac_f32_e32 v90, v91, v90
	v_div_scale_f32 v91, vcc, 1.0, v88, 1.0
	v_mul_f32_e32 v92, v91, v90
	v_fma_f32 v93, -v89, v92, v91
	v_fmac_f32_e32 v92, v93, v90
	v_fma_f32 v89, -v89, v92, v91
	v_div_fmas_f32 v89, v89, v90, v92
	v_div_fixup_f32 v88, v89, v88, 1.0
	v_mul_f32_e32 v89, v118, v84
	v_mul_f32_e32 v90, v89, v89
	s_nop 1
	v_mov_b32_dpp v90, v90 quad_perm:[1,0,3,2] row_mask:0xf bank_mask:0xf bound_ctrl:1
	v_fmac_f32_e32 v90, v89, v89
	s_nop 1
	v_add_f32_dpp v90, v90, v90 quad_perm:[2,3,0,1] row_mask:0xf bank_mask:0xf bound_ctrl:1
	s_nop 1
	v_add_f32_dpp v90, v90, v90 row_half_mirror row_mask:0xf bank_mask:0xf bound_ctrl:1
	s_nop 1
	v_add_f32_dpp v90, v90, v90 row_mirror row_mask:0xf bank_mask:0xf bound_ctrl:1
	s_nop 0
	v_readlane_b32 s1, v90, 16
	v_readlane_b32 s0, v90, 0
	s_nop 0
	v_mov_b32_e32 v91, s1
	v_readlane_b32 s1, v90, 48
	v_add_f32_e32 v91, s0, v91
	v_readlane_b32 s0, v90, 32
	v_mov_b32_e32 v90, s1
	s_nop 0
	v_add_f32_e32 v90, s0, v90
	v_add_f32_e32 v90, v91, v90
	v_cmp_gt_f32_e32 vcc, s7, v90
	v_mul_f32_e32 v91, 0x4f800000, v90
	s_nop 0
	v_cndmask_b32_e32 v90, v90, v91, vcc
	v_sqrt_f32_e32 v91, v90
	s_nop 0
	v_add_u32_e32 v92, -1, v91
	v_fma_f32 v93, -v92, v91, v90
	v_cmp_ge_f32_e64 s[0:1], 0, v93
	v_add_u32_e32 v93, 1, v91
	s_nop 0
	v_cndmask_b32_e64 v92, v91, v92, s[0:1]
	v_fma_f32 v91, -v93, v91, v90
	v_cmp_lt_f32_e64 s[0:1], 0, v91
	s_nop 1
	v_cndmask_b32_e64 v91, v92, v93, s[0:1]
	v_mul_f32_e32 v92, 0x37800000, v91
	v_cndmask_b32_e32 v91, v91, v92, vcc
	v_cmp_class_f32_e32 vcc, v90, v207
	s_nop 1
	v_cndmask_b32_e32 v90, v91, v90, vcc
	v_max_f32_e32 v90, 0x2b8cbccc, v90
	v_div_scale_f32 v91, s[0:1], v90, v90, v89
	v_rcp_f32_e32 v92, v91
	s_nop 0
	v_fma_f32 v93, -v91, v92, 1.0
	v_fmac_f32_e32 v92, v93, v92
	v_div_scale_f32 v93, vcc, v89, v90, v89
	v_mul_f32_e32 v115, v93, v92
	v_fma_f32 v144, -v91, v115, v93
	v_fmac_f32_e32 v115, v144, v92
	v_fma_f32 v91, -v91, v115, v93
	v_div_fmas_f32 v91, v91, v92, v115
	v_div_fixup_f32 v90, v91, v90, v89
	v_add_f32_e32 v89, -1.0, v88
	v_fma_f32 v89, v119, v89, 1.0
	v_mul_f32_e32 v84, v84, v89
	v_mul_f32_e32 v91, v88, v90
	v_mul_f32_e32 v88, v83, v84
	v_mul_f32_e32 v89, v120, v88
	s_nop 1
	v_mov_b32_dpp v89, v89 quad_perm:[1,0,3,2] row_mask:0xf bank_mask:0xf bound_ctrl:1
	v_fmac_f32_e32 v89, v120, v88
	s_nop 1
	v_add_f32_dpp v88, v89, v89 quad_perm:[2,3,0,1] row_mask:0xf bank_mask:0xf bound_ctrl:1
	s_nop 1
	v_add_f32_dpp v88, v88, v88 row_half_mirror row_mask:0xf bank_mask:0xf bound_ctrl:1
	s_nop 1
	v_add_f32_dpp v88, v88, v88 row_mirror row_mask:0xf bank_mask:0xf bound_ctrl:1
	s_nop 0
	v_readlane_b32 s0, v88, 0
	v_readlane_b32 s11, v88, 16
	v_readlane_b32 s1, v88, 32
	v_readlane_b32 s13, v88, 48
	v_mad_i64_i32 v[88:89], s[2:3], s37, v143, v[104:105]
	global_store_dword v[88:89], v90, off nt
	global_store_dword v[88:89], v91, off offset:256 nt
	global_store_dword v[88:89], v82, off offset:512 nt
	global_store_dword v[88:89], v84, off offset:768 nt
	global_store_dword v[88:89], v83, off offset:1024 nt
	global_store_dword v[88:89], v85, off offset:1280 nt
	s_and_saveexec_b64 s[2:3], s[42:43]
	s_cbranch_execz .LBB0_100
	s_add_i32 vcc_lo, s19, s31
	s_ashr_i32 vcc_hi, vcc_lo, 31
	s_lshl_b64 vcc, vcc, 2
	s_add_u32 vcc_lo, s9, vcc_lo
	v_mov_b32_e32 v82, s11
	v_mov_b32_e32 v83, s13
	s_addc_u32 vcc_hi, s15, vcc_hi
	v_pk_add_f32 v[82:83], s[0:1], v[82:83]
	s_nop 0
	v_add_f32_e32 v84, v82, v83
	v_mov_b64_e32 v[82:83], vcc
	global_store_dword v[82:83], v84, off
; #define LAS __attribute__((address_space(3)))
; __device__ __forceinline__ void phase_prep(const Args& A, const Ctx& C0, int l) {
;     ...
;         for (int tt = 0; tt < 8; ++tt) {
;             const float aw = outw[tt * 512 + c], aa = outa[tt * 512 + c];
;             const int row = row0 + tt;
;             const LAS float* cu = raw + (tt + 1) * DSH; const LAS float* pv = raw + tt * DSH;
;             const float r = cu[c] + (pv[c] - cu[c]) * mu_r, k = cu[512 + c] + (pv[512 + c] - cu[512 + c]) * mu_k, v = cu[1024 + c] + (pv[1024 + c] - cu[1024 + c]) * mu_v;
;             const float lw = w0 + aw; const float z = -lw;
;             const float sp = fmaxf(z, 0.f) + logf(1.f + expf(-fabsf(z)));
;             const float wraw = -sp - 0.5f; const float decay = expf(-expf(wraw));
;             const float ai = 1.f / (1.f + expf(-(a0 + aa)));
;             const float kkr = k * kkc; const float ss = wave_sum_l(kkr * kkr, C.lane);
;             const float kk = kkr / fmaxf(sqrtf(ss), 1e-12f);
;             const float k2 = k * (1.f + (ai - 1.f) * kac); const float b = kk * ai;
;             const float rk = wave_sum_l(r * k2 * rkc, C.lane);
;             float* s = SCN + (size_t)row * 3072 + head * 384 + C.lane;
;             __builtin_nontemporal_store(kk, s); __builtin_nontemporal_store(b, s + 64); __builtin_nontemporal_store(decay, s + 128); __builtin_nontemporal_store(k2, s + 192); __builtin_nontemporal_store(r, s + 256); __builtin_nontemporal_store(v, s + 320);
;             if (C.lane == 0) RKB[row * 8 + head] = rk;
.LBB0_100:
	s_or_b64 exec, exec, s[2:3]
	v_add_u32_e32 v82, 0x10300, v87
	ds_read_b32 v90, v82
	v_add_u32_e32 v82, 0x14300, v87
	ds_read_b32 v87, v82
	ds_read2st64_b32 v[82:83], v86 offset0:42 offset1:52
	ds_read2st64_b32 v[88:89], v86 offset0:26 offset1:34
	ds_read2st64_b32 v[84:85], v86 offset0:60 offset1:68
	s_add_i32 s2, s37, 1
	s_waitcnt lgkmcnt(0)
	v_sub_f32_e32 v88, v88, v83
	v_sub_f32_e32 v82, v82, v85
	v_fmac_f32_e32 v85, v123, v82
	v_add_f32_e32 v82, v116, v90
	v_fmac_f32_e32 v83, v121, v88
	v_mul_f32_e64 v88, |v82|, s20
	v_sub_f32_e32 v86, v89, v84
	v_fma_f32 v89, |v82|, s20, -v88
	v_rndne_f32_e32 v90, v88
	v_fma_f32 v89, |v82|, s21, v89
	v_sub_f32_e32 v88, v88, v90
	v_add_f32_e32 v88, v88, v89
	v_exp_f32_e32 v88, v88
	v_cvt_i32_f32_e32 v89, v90
	v_cmp_ngt_f32_e64 vcc, |v82|, s28
	v_fma_f32 v84, v122, v86, v84
	v_max_f32_e64 v86, -v82, 0
	v_ldexp_f32 v88, v88, v89
	v_cndmask_b32_e32 v88, 0, v88, vcc
	v_cmp_nlt_f32_e64 vcc, |v82|, s29
	s_nop 1
	v_cndmask_b32_e32 v82, v251, v88, vcc
	v_add_f32_e32 v82, 1.0, v82
	v_cmp_gt_f32_e32 vcc, s35, v82
	s_nop 1
	v_cndmask_b32_e64 v88, 0, 32, vcc
	v_ldexp_f32 v82, v82, v88
	v_log_f32_e32 v82, v82
	s_nop 0
	v_mul_f32_e32 v88, 0x3f317217, v82
	v_fma_f32 v88, v82, s4, -v88
	v_fmac_f32_e32 v88, 0x3377d1cf, v82
	v_fmac_f32_e32 v88, 0x3f317217, v82
	v_cmp_lt_f32_e64 s[0:1], |v82|, s34
	s_nop 1
	v_cndmask_b32_e64 v82, v82, v88, s[0:1]
	v_cndmask_b32_e32 v88, 0, v142, vcc
	v_sub_f32_e32 v82, v82, v88
	v_add_f32_e32 v82, v86, v82
	v_sub_f32_e32 v82, -0.5, v82
	v_mul_f32_e32 v86, 0x3fb8aa3b, v82
	v_fma_f32 v88, v82, s97, -v86
	v_rndne_f32_e32 v89, v86
	v_fmac_f32_e32 v88, 0x32a5705f, v82
	v_sub_f32_e32 v86, v86, v89
	v_add_f32_e32 v86, v86, v88
	v_exp_f32_e32 v86, v86
	v_cvt_i32_f32_e32 v88, v89
	v_cmp_ngt_f32_e32 vcc, s5, v82
	v_ldexp_f32 v86, v86, v88
	s_nop 0
	v_cndmask_b32_e32 v86, 0, v86, vcc
	v_cmp_nlt_f32_e32 vcc, s6, v82
	s_nop 1
	v_cndmask_b32_e32 v82, v251, v86, vcc
	v_mul_f32_e32 v86, 0xbfb8aa3b, v82
	v_fma_f32 v88, v82, s20, -v86
	v_rndne_f32_e32 v89, v86
	v_fmac_f32_e32 v88, 0xb2a5705f, v82
	v_sub_f32_e32 v86, v86, v89
	v_add_f32_e32 v86, v86, v88
	v_exp_f32_e32 v86, v86
	v_cvt_i32_f32_e32 v88, v89
	v_cmp_nlt_f32_e32 vcc, s28, v82
	v_ldexp_f32 v86, v86, v88
	s_nop 0
	v_cndmask_b32_e32 v86, 0, v86, vcc
	v_cmp_ngt_f32_e32 vcc, s29, v82
	s_nop 1
	v_cndmask_b32_e32 v82, v251, v86, vcc
	v_add_f32_e32 v86, v117, v87
	v_mul_f32_e32 v87, 0xbfb8aa3b, v86
	v_fma_f32 v88, v86, s20, -v87
	v_rndne_f32_e32 v89, v87
	v_fmac_f32_e32 v88, 0xb2a5705f, v86
	v_sub_f32_e32 v87, v87, v89
	v_add_f32_e32 v87, v87, v88
	v_exp_f32_e32 v87, v87
	v_cvt_i32_f32_e32 v88, v89
	v_cmp_nlt_f32_e32 vcc, s28, v86
	v_ldexp_f32 v87, v87, v88
	s_nop 0
	v_cndmask_b32_e32 v87, 0, v87, vcc
	v_cmp_ngt_f32_e32 vcc, s29, v86
	s_nop 1
	v_cndmask_b32_e32 v86, v251, v87, vcc
	v_add_f32_e32 v86, 1.0, v86
	v_div_scale_f32 v87, s[0:1], v86, v86, 1.0
	v_rcp_f32_e32 v88, v87
	s_nop 0
	v_fma_f32 v89, -v87, v88, 1.0
	v_fmac_f32_e32 v88, v89, v88
	v_div_scale_f32 v89, vcc, 1.0, v86, 1.0
	v_mul_f32_e32 v90, v89, v88
	v_fma_f32 v91, -v87, v90, v89
	v_fmac_f32_e32 v90, v91, v88
	v_fma_f32 v87, -v87, v90, v89
	v_div_fmas_f32 v87, v87, v88, v90
	v_div_fixup_f32 v86, v87, v86, 1.0
	v_mul_f32_e32 v87, v118, v84
	v_mul_f32_e32 v88, v87, v87
	s_nop 1
	v_mov_b32_dpp v88, v88 quad_perm:[1,0,3,2] row_mask:0xf bank_mask:0xf bound_ctrl:1
	v_fmac_f32_e32 v88, v87, v87
	s_nop 1
	v_add_f32_dpp v88, v88, v88 quad_perm:[2,3,0,1] row_mask:0xf bank_mask:0xf bound_ctrl:1
	s_nop 1
	v_add_f32_dpp v88, v88, v88 row_half_mirror row_mask:0xf bank_mask:0xf bound_ctrl:1
	s_nop 1
	v_add_f32_dpp v88, v88, v88 row_mirror row_mask:0xf bank_mask:0xf bound_ctrl:1
	s_nop 0
	v_readlane_b32 s1, v88, 16
	v_readlane_b32 s0, v88, 0
	s_nop 0
	v_mov_b32_e32 v89, s1
	v_readlane_b32 s1, v88, 48
	v_add_f32_e32 v89, s0, v89
	v_readlane_b32 s0, v88, 32
	v_mov_b32_e32 v88, s1
	s_nop 0
	v_add_f32_e32 v88, s0, v88
	v_add_f32_e32 v88, v89, v88
	v_cmp_gt_f32_e32 vcc, s7, v88
	v_mul_f32_e32 v89, 0x4f800000, v88
	s_nop 0
	v_cndmask_b32_e32 v88, v88, v89, vcc
	v_sqrt_f32_e32 v89, v88
	s_nop 0
	v_add_u32_e32 v90, -1, v89
	v_fma_f32 v91, -v90, v89, v88
	v_cmp_ge_f32_e64 s[0:1], 0, v91
	v_add_u32_e32 v91, 1, v89
	s_nop 0
	v_cndmask_b32_e64 v90, v89, v90, s[0:1]
	v_fma_f32 v89, -v91, v89, v88
	v_cmp_lt_f32_e64 s[0:1], 0, v89
	s_nop 1
	v_cndmask_b32_e64 v89, v90, v91, s[0:1]
	v_mul_f32_e32 v90, 0x37800000, v89
	v_cndmask_b32_e32 v89, v89, v90, vcc
	v_cmp_class_f32_e32 vcc, v88, v207
	s_nop 1
	v_cndmask_b32_e32 v88, v89, v88, vcc
	v_max_f32_e32 v88, 0x2b8cbccc, v88
	v_div_scale_f32 v89, s[0:1], v88, v88, v87
	v_rcp_f32_e32 v90, v89
	s_nop 0
	v_fma_f32 v91, -v89, v90, 1.0
	v_fmac_f32_e32 v90, v91, v90
	v_div_scale_f32 v91, vcc, v87, v88, v87
	v_mul_f32_e32 v92, v91, v90
	v_fma_f32 v93, -v89, v92, v91
	v_fmac_f32_e32 v92, v93, v90
	v_fma_f32 v89, -v89, v92, v91
	v_div_fmas_f32 v89, v89, v90, v92
	v_div_fixup_f32 v88, v89, v88, v87
	v_add_f32_e32 v87, -1.0, v86
	v_fma_f32 v87, v119, v87, 1.0
	v_mul_f32_e32 v84, v84, v87
	v_mul_f32_e32 v89, v86, v88
	v_mul_f32_e32 v86, v83, v84
	v_mul_f32_e32 v87, v120, v86
	s_nop 1
	v_mov_b32_dpp v87, v87 quad_perm:[1,0,3,2] row_mask:0xf bank_mask:0xf bound_ctrl:1
	v_fmac_f32_e32 v87, v120, v86
	s_nop 1
	v_add_f32_dpp v86, v87, v87 quad_perm:[2,3,0,1] row_mask:0xf bank_mask:0xf bound_ctrl:1
	s_nop 1
	v_add_f32_dpp v86, v86, v86 row_half_mirror row_mask:0xf bank_mask:0xf bound_ctrl:1
	s_nop 1
	v_add_f32_dpp v86, v86, v86 row_mirror row_mask:0xf bank_mask:0xf bound_ctrl:1
	s_nop 0
	v_readlane_b32 s0, v86, 0
	v_readlane_b32 s11, v86, 16
	v_readlane_b32 s1, v86, 32
	v_readlane_b32 s13, v86, 48
	v_mad_i64_i32 v[86:87], s[2:3], s2, v143, v[104:105]
	global_store_dword v[86:87], v88, off nt
	global_store_dword v[86:87], v89, off offset:256 nt
	global_store_dword v[86:87], v82, off offset:512 nt
	global_store_dword v[86:87], v84, off offset:768 nt
	global_store_dword v[86:87], v83, off offset:1024 nt
	global_store_dword v[86:87], v85, off offset:1280 nt
	s_and_saveexec_b64 s[2:3], s[42:43]
	s_cbranch_execz .LBB0_97
	s_add_i32 s75, s19, s31
	s_add_i32 vcc_lo, s75, 8
	s_ashr_i32 vcc_hi, vcc_lo, 31
	s_lshl_b64 vcc, vcc, 2
	s_add_u32 vcc_lo, s9, vcc_lo
	v_mov_b32_e32 v82, s11
	v_mov_b32_e32 v83, s13
	s_addc_u32 vcc_hi, s15, vcc_hi
	v_pk_add_f32 v[82:83], s[0:1], v[82:83]
	s_nop 0
	v_add_f32_e32 v84, v82, v83
	v_mov_b64_e32 v[82:83], vcc
	global_store_dword v[82:83], v84, off
	s_branch .LBB0_97

; __device__ __forceinline__ unsigned cvt_pk_bf16(float lo, float hi) { unsigned r; asm volatile("v_cvt_pk_bf16_f32 %0, %1, %2" : "=v"(r) : "v"(lo), "v"(hi)); return r; }
;     __device__ __forceinline__ void operator()(const f32x4 (&acc)[2][2][4][2], const Unit& u, int wr, int wc, int fr, int fq) const {
;         const int row0 = u.pm * BM + wr * 64 + fr; const int col0 = u.pn * BM + wc * 32 + 8 * fq;
; #pragma unroll
;         for (int ai = 0; ai < 2; ++ai)
; #pragma unroll
;             for (int m = 0; m < 4; ++m) { bf16_t* rowp = O + (size_t)(row0 + ai * HALF + m * 16) * 5504 + col0;
;                 const float rs = 1.0f / sqrtf(SS[row0 + ai * HALF + m * 16] * (1.0f / 2048.0f) + 1e-5f);
; #pragma unroll
;                 for (int bj = 0; bj < 2; ++bj) { if (u.pn * BM + bj * HALF < 5504) { const f32x4 v0 = acc[ai][bj][m][0] * rs, v1 = acc[ai][bj][m][1] * rs;
;                     u32x4 w; w.x = cvt_pk_bf16(v0[0], v0[1]); w.y = cvt_pk_bf16(v0[2], v0[3]); w.z = cvt_pk_bf16(v1[0], v1[1]); w.w = cvt_pk_bf16(v1[2], v1[3]);
;                     *(u32x4*)(rowp + bj * HALF) = w; } } }
.LBB0_1275:
	s_lshl_b32 s2, s24, 8
	v_or_b32_e32 v146, s2, v158
	v_lshl_add_u32 v148, s40, 8, v156
	v_mov_b64_e32 v[150:151], s[46:47]
	s_movk_i32 s0, 0x2b00
	v_ashrrev_i32_e32 v147, 31, v146
	v_ashrrev_i32_e32 v149, 31, v148
	v_mad_i64_i32 v[150:151], s[0:1], v148, s0, v[150:151]
	v_lshl_add_u64 v[152:153], v[146:147], 1, v[150:151]
	v_lshl_add_u64 v[150:151], v[148:149], 2, s[36:37]
	global_load_dword v232, v[150:151], off
	global_load_dword v233, v[150:151], off offset:64
	global_load_dword v234, v[150:151], off offset:128
	global_load_dword v235, v[150:151], off offset:192
	global_load_dword v236, v[150:151], off offset:512
	global_load_dword v237, v[150:151], off offset:576
	global_load_dword v238, v[150:151], off offset:640
	global_load_dword v239, v[150:151], off offset:704
	s_cmp_lt_i32 s24, 22
	s_cselect_b64 s[42:43], -1, 0
	s_cmp_gt_i32 s24, 21
	s_waitcnt vmcnt(0)
	v_fmamk_f32 v149, v232, 0x3a000000, v229
	v_cmp_gt_f32_e32 vcc, s7, v149
	v_mul_f32_e32 v154, 0x4f800000, v149
	s_nop 0
	v_cndmask_b32_e32 v149, v149, v154, vcc
	v_sqrt_f32_e32 v154, v149
	s_nop 0
	v_add_u32_e32 v155, -1, v154
	v_fma_f32 v160, -v155, v154, v149
	v_cmp_ge_f32_e64 s[0:1], 0, v160
	v_add_u32_e32 v160, 1, v154
	s_nop 0
	v_cndmask_b32_e64 v155, v154, v155, s[0:1]
	v_fma_f32 v154, -v160, v154, v149
	v_cmp_lt_f32_e64 s[0:1], 0, v154
	s_nop 1
	v_cndmask_b32_e64 v154, v155, v160, s[0:1]
	v_mul_f32_e32 v155, 0x37800000, v154
	v_cndmask_b32_e32 v154, v154, v155, vcc
	v_cmp_class_f32_e32 vcc, v149, v207
	s_nop 1
	v_cndmask_b32_e32 v149, v154, v149, vcc
	v_div_scale_f32 v154, s[0:1], v149, v149, 1.0
	v_rcp_f32_e32 v155, v154
	s_nop 0
	v_fma_f32 v160, -v154, v155, 1.0
	v_fmac_f32_e32 v155, v160, v155
	v_div_scale_f32 v160, vcc, 1.0, v149, 1.0
	v_mul_f32_e32 v161, v160, v155
	v_fma_f32 v162, -v154, v161, v160
	v_fmac_f32_e32 v161, v162, v155
	v_fma_f32 v154, -v154, v161, v160
	v_div_fmas_f32 v154, v154, v155, v161
	v_div_fixup_f32 v154, v154, v149, 1.0
	v_mov_b32_e32 v155, v154
	s_cbranch_scc1 .LBB0_1277
	v_mov_b32_e32 v160, v154
	v_mov_b32_e32 v161, v154
	v_pk_mul_f32 v[132:133], v[132:133], v[160:161]
	v_pk_mul_f32 v[160:161], v[128:129], v[160:161]
	v_pk_mul_f32 v[128:129], v[126:127], v[154:155]
	v_pk_mul_f32 v[130:131], v[130:131], v[154:155]
	s_nop 0
	v_cvt_pk_bf16_f32 v126, v130, v131
	v_cvt_pk_bf16_f32 v127, v132, v133
	v_cvt_pk_bf16_f32 v128, v128, v129
	v_cvt_pk_bf16_f32 v129, v160, v161
	global_store_dwordx4 v[152:153], v[126:129], off
.LBB0_1277:
	s_bitset1_b32 s2, 7
	s_cmpk_gt_i32 s2, 0x157f
	s_cbranch_scc1 .LBB0_1279
	v_mov_b32_e32 v126, v154
	v_mov_b32_e32 v127, v154
	v_pk_mul_f32 v[124:125], v[124:125], v[126:127]
	v_pk_mul_f32 v[126:127], v[120:121], v[126:127]
	v_pk_mul_f32 v[120:121], v[118:119], v[154:155]
	v_pk_mul_f32 v[122:123], v[122:123], v[154:155]
	s_nop 0
	v_cvt_pk_bf16_f32 v118, v122, v123
	v_cvt_pk_bf16_f32 v119, v124, v125
	v_cvt_pk_bf16_f32 v120, v120, v121
	v_cvt_pk_bf16_f32 v121, v126, v127
	global_store_dwordx4 v[152:153], v[118:121], off offset:256
.LBB0_1279:
	s_nop 0
	s_nop 0
	v_or_b32_e32 v121, 16, v148
	v_mov_b64_e32 v[118:119], s[46:47]
	s_movk_i32 s0, 0x2b00
	v_cndmask_b32_e64 v122, 0, 1, s[42:43]
	v_mad_i64_i32 v[118:119], s[0:1], v121, s0, v[118:119]
	v_cmp_ne_u32_e64 s[40:41], 1, v122
	v_lshl_add_u64 v[118:119], v[146:147], 1, v[118:119]
	v_fmamk_f32 v120, v233, 0x3a000000, v229
	v_mul_f32_e32 v123, 0x4f800000, v120
	v_cmp_gt_f32_e32 vcc, s7, v120
	s_nop 1
	v_cndmask_b32_e32 v120, v120, v123, vcc
	v_sqrt_f32_e32 v123, v120
	s_nop 0
	v_add_u32_e32 v121, -1, v123
	v_add_u32_e32 v122, 1, v123
	v_fma_f32 v124, -v121, v123, v120
	v_fma_f32 v125, -v122, v123, v120
	v_cmp_ge_f32_e64 s[0:1], 0, v124
	s_nop 1
	v_cndmask_b32_e64 v121, v123, v121, s[0:1]
	v_cmp_lt_f32_e64 s[0:1], 0, v125
	s_nop 1
	v_cndmask_b32_e64 v121, v121, v122, s[0:1]
	v_mul_f32_e32 v122, 0x37800000, v121
	v_cndmask_b32_e32 v121, v121, v122, vcc
	v_cmp_class_f32_e32 vcc, v120, v207
	s_nop 1
	v_cndmask_b32_e32 v120, v121, v120, vcc
	v_div_scale_f32 v121, s[0:1], v120, v120, 1.0
	v_rcp_f32_e32 v122, v121
	v_div_scale_f32 v123, vcc, 1.0, v120, 1.0
	v_fma_f32 v124, -v121, v122, 1.0
	v_fmac_f32_e32 v122, v124, v122
	v_mul_f32_e32 v124, v123, v122
	v_fma_f32 v125, -v121, v124, v123
	v_fmac_f32_e32 v124, v125, v122
	v_fma_f32 v121, -v121, v124, v123
	v_div_fmas_f32 v121, v121, v122, v124
	v_div_fixup_f32 v120, v121, v120, 1.0
	s_andn2_b64 vcc, exec, s[42:43]
	v_mov_b32_e32 v121, v120
	s_cbranch_vccnz .LBB0_1281
	v_mov_b32_e32 v122, v120
	v_mov_b32_e32 v123, v120
	v_pk_mul_f32 v[116:117], v[116:117], v[122:123]
	v_pk_mul_f32 v[122:123], v[112:113], v[122:123]
	v_pk_mul_f32 v[112:113], v[110:111], v[120:121]
	v_pk_mul_f32 v[114:115], v[114:115], v[120:121]
	s_nop 0
	v_cvt_pk_bf16_f32 v110, v114, v115
	v_cvt_pk_bf16_f32 v111, v116, v117
	v_cvt_pk_bf16_f32 v112, v112, v113
	v_cvt_pk_bf16_f32 v113, v122, v123
	global_store_dwordx4 v[118:119], v[110:113], off
.LBB0_1281:
	s_cmp_lt_i32 s24, 21
	s_cselect_b64 s[42:43], -1, 0
	s_cmp_gt_i32 s24, 20
	s_cbranch_scc1 .LBB0_1283
	v_mov_b32_e32 v110, v120
	v_mov_b32_e32 v111, v120
	v_pk_mul_f32 v[108:109], v[108:109], v[110:111]
	v_pk_mul_f32 v[110:111], v[104:105], v[110:111]
	v_pk_mul_f32 v[104:105], v[102:103], v[120:121]
	v_pk_mul_f32 v[106:107], v[106:107], v[120:121]
	s_nop 0
	v_cvt_pk_bf16_f32 v102, v106, v107
	v_cvt_pk_bf16_f32 v103, v108, v109
	v_cvt_pk_bf16_f32 v104, v104, v105
	v_cvt_pk_bf16_f32 v105, v110, v111
	global_store_dwordx4 v[118:119], v[102:105], off offset:256
; __device__ __forceinline__ unsigned cvt_pk_bf16(float lo, float hi) { unsigned r; asm volatile("v_cvt_pk_bf16_f32 %0, %1, %2" : "=v"(r) : "v"(lo), "v"(hi)); return r; }
;     __device__ __forceinline__ void operator()(const f32x4 (&acc)[2][2][4][2], const Unit& u, int wr, int wc, int fr, int fq) const {
;         const int row0 = u.pm * BM + wr * 64 + fr; const int col0 = u.pn * BM + wc * 32 + 8 * fq;
; #pragma unroll
;         for (int ai = 0; ai < 2; ++ai)
; #pragma unroll
;             for (int m = 0; m < 4; ++m) { bf16_t* rowp = O + (size_t)(row0 + ai * HALF + m * 16) * 5504 + col0;
;                 const float rs = 1.0f / sqrtf(SS[row0 + ai * HALF + m * 16] * (1.0f / 2048.0f) + 1e-5f);
; #pragma unroll
;                 for (int bj = 0; bj < 2; ++bj) { if (u.pn * BM + bj * HALF < 5504) { const f32x4 v0 = acc[ai][bj][m][0] * rs, v1 = acc[ai][bj][m][1] * rs;
;                     u32x4 w; w.x = cvt_pk_bf16(v0[0], v0[1]); w.y = cvt_pk_bf16(v0[2], v0[3]); w.z = cvt_pk_bf16(v1[0], v1[1]); w.w = cvt_pk_bf16(v1[2], v1[3]);
;                     *(u32x4*)(rowp + bj * HALF) = w; } } }
.LBB0_1283:
	s_nop 0
	s_nop 0
	v_or_b32_e32 v104, 32, v148
	s_movk_i32 s0, 0x2b00
	v_fmamk_f32 v102, v234, 0x3a000000, v229
	v_mul_f32_e32 v103, 0x4f800000, v102
	v_cmp_gt_f32_e32 vcc, s7, v102
	s_nop 1
	v_cndmask_b32_e32 v105, v102, v103, vcc
	v_sqrt_f32_e32 v106, v105
	v_mov_b64_e32 v[102:103], s[46:47]
	v_mad_i64_i32 v[102:103], s[0:1], v104, s0, v[102:103]
	v_add_u32_e32 v104, -1, v106
	v_add_u32_e32 v107, 1, v106
	v_fma_f32 v108, -v104, v106, v105
	v_fma_f32 v109, -v107, v106, v105
	v_cmp_ge_f32_e64 s[0:1], 0, v108
	v_lshl_add_u64 v[102:103], v[146:147], 1, v[102:103]
	s_nop 0
	v_cndmask_b32_e64 v104, v106, v104, s[0:1]
	v_cmp_lt_f32_e64 s[0:1], 0, v109
	s_nop 1
	v_cndmask_b32_e64 v104, v104, v107, s[0:1]
	v_mul_f32_e32 v106, 0x37800000, v104
	v_cndmask_b32_e32 v104, v104, v106, vcc
	v_cmp_class_f32_e32 vcc, v105, v207
	s_nop 1
	v_cndmask_b32_e32 v104, v104, v105, vcc
	v_div_scale_f32 v105, s[0:1], v104, v104, 1.0
	v_rcp_f32_e32 v106, v105
	v_div_scale_f32 v107, vcc, 1.0, v104, 1.0
	v_fma_f32 v108, -v105, v106, 1.0
	v_fmac_f32_e32 v106, v108, v106
	v_mul_f32_e32 v108, v107, v106
	v_fma_f32 v109, -v105, v108, v107
	v_fmac_f32_e32 v108, v109, v106
	v_fma_f32 v105, -v105, v108, v107
	v_div_fmas_f32 v105, v105, v106, v108
	v_div_fixup_f32 v104, v105, v104, 1.0
	s_and_b64 vcc, exec, s[40:41]
	v_mov_b32_e32 v105, v104
	s_cbranch_vccnz .LBB0_1285
	v_mov_b32_e32 v106, v104
	v_mov_b32_e32 v107, v104
	v_pk_mul_f32 v[96:97], v[96:97], v[106:107]
	v_pk_mul_f32 v[106:107], v[92:93], v[106:107]
	v_pk_mul_f32 v[92:93], v[90:91], v[104:105]
	v_pk_mul_f32 v[94:95], v[94:95], v[104:105]
	s_nop 0
	v_cvt_pk_bf16_f32 v90, v94, v95
	v_cvt_pk_bf16_f32 v91, v96, v97
	v_cvt_pk_bf16_f32 v92, v92, v93
	v_cvt_pk_bf16_f32 v93, v106, v107
	global_store_dwordx4 v[102:103], v[90:93], off
.LBB0_1285:
	s_nop 1
	v_cndmask_b32_e64 v90, 0, 1, s[42:43]
	v_cmp_ne_u32_e64 s[0:1], 1, v90
	s_andn2_b64 vcc, exec, s[42:43]
	s_cbranch_vccnz .LBB0_1287
	v_mov_b32_e32 v90, v104
	v_mov_b32_e32 v91, v104
	v_pk_mul_f32 v[88:89], v[88:89], v[90:91]
	v_pk_mul_f32 v[90:91], v[84:85], v[90:91]
	v_pk_mul_f32 v[84:85], v[82:83], v[104:105]
	v_pk_mul_f32 v[86:87], v[86:87], v[104:105]
	s_nop 0
	v_cvt_pk_bf16_f32 v82, v86, v87
	v_cvt_pk_bf16_f32 v83, v88, v89
	v_cvt_pk_bf16_f32 v84, v84, v85
	v_cvt_pk_bf16_f32 v85, v90, v91
	global_store_dwordx4 v[102:103], v[82:85], off offset:256
.LBB0_1287:
	s_nop 0
	s_nop 0
	v_or_b32_e32 v84, 48, v148
	s_movk_i32 s2, 0x2b00
	v_fmamk_f32 v82, v235, 0x3a000000, v229
	v_mul_f32_e32 v83, 0x4f800000, v82
	v_cmp_gt_f32_e32 vcc, s7, v82
	s_nop 1
	v_cndmask_b32_e32 v85, v82, v83, vcc
	v_sqrt_f32_e32 v86, v85
	v_mov_b64_e32 v[82:83], s[46:47]
	v_mad_i64_i32 v[82:83], s[2:3], v84, s2, v[82:83]
	v_add_u32_e32 v84, -1, v86
	v_add_u32_e32 v87, 1, v86
	v_fma_f32 v88, -v84, v86, v85
	v_fma_f32 v89, -v87, v86, v85
	v_cmp_ge_f32_e64 s[42:43], 0, v88
	v_lshl_add_u64 v[82:83], v[146:147], 1, v[82:83]
	s_nop 0
	v_cndmask_b32_e64 v84, v86, v84, s[42:43]
	v_cmp_lt_f32_e64 s[42:43], 0, v89
	s_nop 1
	v_cndmask_b32_e64 v84, v84, v87, s[42:43]
	v_mul_f32_e32 v86, 0x37800000, v84
	v_cndmask_b32_e32 v84, v84, v86, vcc
	v_cmp_class_f32_e32 vcc, v85, v207
	s_nop 1
	v_cndmask_b32_e32 v84, v84, v85, vcc
	v_div_scale_f32 v85, s[2:3], v84, v84, 1.0
	v_rcp_f32_e32 v86, v85
	v_div_scale_f32 v87, vcc, 1.0, v84, 1.0
	v_fma_f32 v88, -v85, v86, 1.0
	v_fmac_f32_e32 v86, v88, v86
	v_mul_f32_e32 v88, v87, v86
	v_fma_f32 v89, -v85, v88, v87
	v_fmac_f32_e32 v88, v89, v86
	v_fma_f32 v85, -v85, v88, v87
	v_div_fmas_f32 v85, v85, v86, v88
	v_div_fixup_f32 v84, v85, v84, 1.0
	s_and_b64 vcc, exec, s[40:41]
	v_mov_b32_e32 v85, v84
	s_cbranch_vccnz .LBB0_1289
	v_mov_b32_e32 v86, v84
	v_mov_b32_e32 v87, v84
	v_pk_mul_f32 v[80:81], v[80:81], v[86:87]
	v_pk_mul_f32 v[86:87], v[76:77], v[86:87]
	v_pk_mul_f32 v[76:77], v[74:75], v[84:85]
	v_pk_mul_f32 v[78:79], v[78:79], v[84:85]
	s_nop 0
	v_cvt_pk_bf16_f32 v74, v78, v79
	v_cvt_pk_bf16_f32 v75, v80, v81
	v_cvt_pk_bf16_f32 v76, v76, v77
	v_cvt_pk_bf16_f32 v77, v86, v87
	global_store_dwordx4 v[82:83], v[74:77], off
.LBB0_1289:
	s_and_b64 vcc, exec, s[0:1]
	s_cbranch_vccnz .LBB0_1291
	v_mov_b32_e32 v74, v84
	v_mov_b32_e32 v75, v84
	v_pk_mul_f32 v[72:73], v[72:73], v[74:75]
	v_pk_mul_f32 v[74:75], v[68:69], v[74:75]
	v_pk_mul_f32 v[68:69], v[66:67], v[84:85]
	v_pk_mul_f32 v[70:71], v[70:71], v[84:85]
	s_nop 0
	v_cvt_pk_bf16_f32 v66, v70, v71
	v_cvt_pk_bf16_f32 v67, v72, v73
	v_cvt_pk_bf16_f32 v68, v68, v69
	v_cvt_pk_bf16_f32 v69, v74, v75
	global_store_dwordx4 v[82:83], v[66:69], off offset:256
; __device__ __forceinline__ unsigned cvt_pk_bf16(float lo, float hi) { unsigned r; asm volatile("v_cvt_pk_bf16_f32 %0, %1, %2" : "=v"(r) : "v"(lo), "v"(hi)); return r; }
;     __device__ __forceinline__ void operator()(const f32x4 (&acc)[2][2][4][2], const Unit& u, int wr, int wc, int fr, int fq) const {
;         const int row0 = u.pm * BM + wr * 64 + fr; const int col0 = u.pn * BM + wc * 32 + 8 * fq;
; #pragma unroll
;         for (int ai = 0; ai < 2; ++ai)
; #pragma unroll
;             for (int m = 0; m < 4; ++m) { bf16_t* rowp = O + (size_t)(row0 + ai * HALF + m * 16) * 5504 + col0;
;                 const float rs = 1.0f / sqrtf(SS[row0 + ai * HALF + m * 16] * (1.0f / 2048.0f) + 1e-5f);
; #pragma unroll
;                 for (int bj = 0; bj < 2; ++bj) { if (u.pn * BM + bj * HALF < 5504) { const f32x4 v0 = acc[ai][bj][m][0] * rs, v1 = acc[ai][bj][m][1] * rs;
;                     u32x4 w; w.x = cvt_pk_bf16(v0[0], v0[1]); w.y = cvt_pk_bf16(v0[2], v0[3]); w.z = cvt_pk_bf16(v1[0], v1[1]); w.w = cvt_pk_bf16(v1[2], v1[3]);
;                     *(u32x4*)(rowp + bj * HALF) = w; } } }
.LBB0_1291:
	s_nop 0
	s_nop 0
	v_add_u32_e32 v68, 0x80, v148
	s_movk_i32 s2, 0x2b00
	v_fmamk_f32 v66, v236, 0x3a000000, v229
	v_mul_f32_e32 v67, 0x4f800000, v66
	v_cmp_gt_f32_e32 vcc, s7, v66
	s_nop 1
	v_cndmask_b32_e32 v69, v66, v67, vcc
	v_sqrt_f32_e32 v70, v69
	v_mov_b64_e32 v[66:67], s[46:47]
	v_mad_i64_i32 v[66:67], s[2:3], v68, s2, v[66:67]
	v_add_u32_e32 v68, -1, v70
	v_add_u32_e32 v71, 1, v70
	v_fma_f32 v72, -v68, v70, v69
	v_fma_f32 v73, -v71, v70, v69
	v_cmp_ge_f32_e64 s[42:43], 0, v72
	v_lshl_add_u64 v[66:67], v[146:147], 1, v[66:67]
	s_nop 0
	v_cndmask_b32_e64 v68, v70, v68, s[42:43]
	v_cmp_lt_f32_e64 s[42:43], 0, v73
	s_nop 1
	v_cndmask_b32_e64 v68, v68, v71, s[42:43]
	v_mul_f32_e32 v70, 0x37800000, v68
	v_cndmask_b32_e32 v68, v68, v70, vcc
	v_cmp_class_f32_e32 vcc, v69, v207
	s_nop 1
	v_cndmask_b32_e32 v68, v68, v69, vcc
	v_div_scale_f32 v69, s[2:3], v68, v68, 1.0
	v_rcp_f32_e32 v70, v69
	v_div_scale_f32 v71, vcc, 1.0, v68, 1.0
	v_fma_f32 v72, -v69, v70, 1.0
	v_fmac_f32_e32 v70, v72, v70
	v_mul_f32_e32 v72, v71, v70
	v_fma_f32 v73, -v69, v72, v71
	v_fmac_f32_e32 v72, v73, v70
	v_fma_f32 v69, -v69, v72, v71
	v_div_fmas_f32 v69, v69, v70, v72
	v_div_fixup_f32 v68, v69, v68, 1.0
	s_and_b64 vcc, exec, s[40:41]
	v_mov_b32_e32 v69, v68
	s_cbranch_vccnz .LBB0_1293
	v_mov_b32_e32 v70, v68
	v_mov_b32_e32 v71, v68
	v_pk_mul_f32 v[64:65], v[64:65], v[70:71]
	v_pk_mul_f32 v[70:71], v[60:61], v[70:71]
	v_pk_mul_f32 v[60:61], v[58:59], v[68:69]
	v_pk_mul_f32 v[62:63], v[62:63], v[68:69]
	s_nop 0
	v_cvt_pk_bf16_f32 v58, v62, v63
	v_cvt_pk_bf16_f32 v59, v64, v65
	v_cvt_pk_bf16_f32 v60, v60, v61
	v_cvt_pk_bf16_f32 v61, v70, v71
	global_store_dwordx4 v[66:67], v[58:61], off
.LBB0_1293:
	s_and_b64 vcc, exec, s[0:1]
	s_cbranch_vccnz .LBB0_1295
	v_mov_b32_e32 v58, v68
	v_mov_b32_e32 v59, v68
	v_pk_mul_f32 v[56:57], v[56:57], v[58:59]
	v_pk_mul_f32 v[58:59], v[52:53], v[58:59]
	v_pk_mul_f32 v[52:53], v[50:51], v[68:69]
	v_pk_mul_f32 v[54:55], v[54:55], v[68:69]
	s_nop 0
	v_cvt_pk_bf16_f32 v50, v54, v55
	v_cvt_pk_bf16_f32 v51, v56, v57
	v_cvt_pk_bf16_f32 v52, v52, v53
	v_cvt_pk_bf16_f32 v53, v58, v59
	global_store_dwordx4 v[66:67], v[50:53], off offset:256
.LBB0_1295:
	s_nop 0
	s_nop 0
	v_add_u32_e32 v52, 0x90, v148
	s_movk_i32 s2, 0x2b00
	v_fmamk_f32 v50, v237, 0x3a000000, v229
	v_mul_f32_e32 v51, 0x4f800000, v50
	v_cmp_gt_f32_e32 vcc, s7, v50
	s_nop 1
	v_cndmask_b32_e32 v53, v50, v51, vcc
	v_sqrt_f32_e32 v54, v53
	v_mov_b64_e32 v[50:51], s[46:47]
	v_mad_i64_i32 v[50:51], s[2:3], v52, s2, v[50:51]
	v_add_u32_e32 v52, -1, v54
	v_add_u32_e32 v55, 1, v54
	v_fma_f32 v56, -v52, v54, v53
	v_fma_f32 v57, -v55, v54, v53
	v_cmp_ge_f32_e64 s[42:43], 0, v56
	v_lshl_add_u64 v[50:51], v[146:147], 1, v[50:51]
	s_nop 0
	v_cndmask_b32_e64 v52, v54, v52, s[42:43]
	v_cmp_lt_f32_e64 s[42:43], 0, v57
	s_nop 1
	v_cndmask_b32_e64 v52, v52, v55, s[42:43]
	v_mul_f32_e32 v54, 0x37800000, v52
	v_cndmask_b32_e32 v52, v52, v54, vcc
	v_cmp_class_f32_e32 vcc, v53, v207
	s_nop 1
	v_cndmask_b32_e32 v52, v52, v53, vcc
	v_div_scale_f32 v53, s[2:3], v52, v52, 1.0
	v_rcp_f32_e32 v54, v53
	v_div_scale_f32 v55, vcc, 1.0, v52, 1.0
	v_fma_f32 v56, -v53, v54, 1.0
	v_fmac_f32_e32 v54, v56, v54
	v_mul_f32_e32 v56, v55, v54
	v_fma_f32 v57, -v53, v56, v55
	v_fmac_f32_e32 v56, v57, v54
	v_fma_f32 v53, -v53, v56, v55
	v_div_fmas_f32 v53, v53, v54, v56
	v_div_fixup_f32 v52, v53, v52, 1.0
	s_and_b64 vcc, exec, s[40:41]
	v_mov_b32_e32 v53, v52
	s_cbranch_vccnz .LBB0_1297
	v_mov_b32_e32 v54, v52
	v_mov_b32_e32 v55, v52
	v_pk_mul_f32 v[48:49], v[48:49], v[54:55]
	v_pk_mul_f32 v[54:55], v[44:45], v[54:55]
	v_pk_mul_f32 v[44:45], v[42:43], v[52:53]
	v_pk_mul_f32 v[46:47], v[46:47], v[52:53]
	s_nop 0
	v_cvt_pk_bf16_f32 v42, v46, v47
	v_cvt_pk_bf16_f32 v43, v48, v49
	v_cvt_pk_bf16_f32 v44, v44, v45
	v_cvt_pk_bf16_f32 v45, v54, v55
	global_store_dwordx4 v[50:51], v[42:45], off
.LBB0_1297:
	s_and_b64 vcc, exec, s[0:1]
	s_cbranch_vccnz .LBB0_1299
	v_mov_b32_e32 v42, v52
	v_mov_b32_e32 v43, v52
	v_pk_mul_f32 v[40:41], v[40:41], v[42:43]
	v_pk_mul_f32 v[42:43], v[36:37], v[42:43]
	v_pk_mul_f32 v[36:37], v[34:35], v[52:53]
	v_pk_mul_f32 v[38:39], v[38:39], v[52:53]
	s_nop 0
	v_cvt_pk_bf16_f32 v34, v38, v39
	v_cvt_pk_bf16_f32 v35, v40, v41
	v_cvt_pk_bf16_f32 v36, v36, v37
	v_cvt_pk_bf16_f32 v37, v42, v43
	global_store_dwordx4 v[50:51], v[34:37], off offset:256
.LBB0_1299:
	s_nop 0
	s_nop 0
	v_add_u32_e32 v36, 0xa0, v148
	s_movk_i32 s2, 0x2b00
	v_fmamk_f32 v34, v238, 0x3a000000, v229
	v_mul_f32_e32 v35, 0x4f800000, v34
	v_cmp_gt_f32_e32 vcc, s7, v34
	s_nop 1
	v_cndmask_b32_e32 v37, v34, v35, vcc
	v_sqrt_f32_e32 v38, v37
	v_mov_b64_e32 v[34:35], s[46:47]
	v_mad_i64_i32 v[34:35], s[2:3], v36, s2, v[34:35]
	v_add_u32_e32 v36, -1, v38
	v_add_u32_e32 v39, 1, v38
	v_fma_f32 v40, -v36, v38, v37
	v_fma_f32 v41, -v39, v38, v37
	v_cmp_ge_f32_e64 s[42:43], 0, v40
	v_lshl_add_u64 v[34:35], v[146:147], 1, v[34:35]
	s_nop 0
	v_cndmask_b32_e64 v36, v38, v36, s[42:43]
	v_cmp_lt_f32_e64 s[42:43], 0, v41
	s_nop 1
	v_cndmask_b32_e64 v36, v36, v39, s[42:43]
	v_mul_f32_e32 v38, 0x37800000, v36
	v_cndmask_b32_e32 v36, v36, v38, vcc
	v_cmp_class_f32_e32 vcc, v37, v207
	s_nop 1
	v_cndmask_b32_e32 v36, v36, v37, vcc
	v_div_scale_f32 v37, s[2:3], v36, v36, 1.0
	v_rcp_f32_e32 v38, v37
	v_div_scale_f32 v39, vcc, 1.0, v36, 1.0
	v_fma_f32 v40, -v37, v38, 1.0
	v_fmac_f32_e32 v38, v40, v38
	v_mul_f32_e32 v40, v39, v38
	v_fma_f32 v41, -v37, v40, v39
	v_fmac_f32_e32 v40, v41, v38
	v_fma_f32 v37, -v37, v40, v39
	v_div_fmas_f32 v37, v37, v38, v40
	v_div_fixup_f32 v36, v37, v36, 1.0
	s_and_b64 vcc, exec, s[40:41]
	v_mov_b32_e32 v37, v36
	s_cbranch_vccz .LBB0_1302
	s_and_b64 vcc, exec, s[0:1]
	s_cbranch_vccz .LBB0_1303

; __device__ __forceinline__ unsigned cvt_pk_bf16(float lo, float hi) { unsigned r; asm volatile("v_cvt_pk_bf16_f32 %0, %1, %2" : "=v"(r) : "v"(lo), "v"(hi)); return r; }
;     __device__ __forceinline__ void operator()(const f32x4 (&acc)[2][2][4][2], const Unit& u, int wr, int wc, int fr, int fq) const {
;         const int row0 = u.pm * BM + wr * 64 + fr; const int col0 = u.pn * BM + wc * 32 + 8 * fq;
; #pragma unroll
;         for (int ai = 0; ai < 2; ++ai)
; #pragma unroll
;             for (int m = 0; m < 4; ++m) { bf16_t* rowp = O + (size_t)(row0 + ai * HALF + m * 16) * 5504 + col0;
;                 const float rs = 1.0f / sqrtf(SS[row0 + ai * HALF + m * 16] * (1.0f / 2048.0f) + 1e-5f);
; #pragma unroll
;                 for (int bj = 0; bj < 2; ++bj) { if (u.pn * BM + bj * HALF < 5504) { const f32x4 v0 = acc[ai][bj][m][0] * rs, v1 = acc[ai][bj][m][1] * rs;
;                     u32x4 w; w.x = cvt_pk_bf16(v0[0], v0[1]); w.y = cvt_pk_bf16(v0[2], v0[3]); w.z = cvt_pk_bf16(v1[0], v1[1]); w.w = cvt_pk_bf16(v1[2], v1[3]);
;                     *(u32x4*)(rowp + bj * HALF) = w; } } }
.LBB0_1302:
	v_mov_b32_e32 v38, v36
	v_mov_b32_e32 v39, v36
	v_pk_mul_f32 v[32:33], v[32:33], v[38:39]
	v_pk_mul_f32 v[38:39], v[28:29], v[38:39]
	v_pk_mul_f32 v[28:29], v[26:27], v[36:37]
	v_pk_mul_f32 v[30:31], v[30:31], v[36:37]
	s_nop 0
	v_cvt_pk_bf16_f32 v26, v30, v31
	v_cvt_pk_bf16_f32 v27, v32, v33
	v_cvt_pk_bf16_f32 v28, v28, v29
	v_cvt_pk_bf16_f32 v29, v38, v39
	global_store_dwordx4 v[34:35], v[26:29], off
	s_and_b64 vcc, exec, s[0:1]
	s_cbranch_vccnz .LBB0_1301
.LBB0_1303:
	v_mov_b32_e32 v26, v36
	v_mov_b32_e32 v27, v36
	v_pk_mul_f32 v[24:25], v[24:25], v[26:27]
	v_pk_mul_f32 v[26:27], v[20:21], v[26:27]
	v_pk_mul_f32 v[20:21], v[18:19], v[36:37]
	v_pk_mul_f32 v[22:23], v[22:23], v[36:37]
	s_nop 0
	v_cvt_pk_bf16_f32 v18, v22, v23
	v_cvt_pk_bf16_f32 v19, v24, v25
	v_cvt_pk_bf16_f32 v20, v20, v21
	v_cvt_pk_bf16_f32 v21, v26, v27
	global_store_dwordx4 v[34:35], v[18:21], off offset:256
	s_and_b64 vcc, exec, s[40:41]
	s_cbranch_vccnz .LBB0_1306
.LBB0_1304:
	v_add_u32_e32 v20, 0xb0, v148
	v_mov_b64_e32 v[18:19], s[46:47]
	s_movk_i32 s0, 0x2b00
	v_mad_i64_i32 v[18:19], s[0:1], v20, s0, v[18:19]
	s_nop 0
	v_lshl_add_u64 v[18:19], v[146:147], 1, v[18:19]
	s_cmp_eq_u32 s24, 21
	v_fmamk_f32 v20, v239, 0x3a000000, v229
	v_cmp_gt_f32_e32 vcc, s7, v20
	v_mul_f32_e32 v21, 0x4f800000, v20
	s_nop 0
	v_cndmask_b32_e32 v20, v20, v21, vcc
	v_sqrt_f32_e32 v21, v20
	s_nop 0
	v_add_u32_e32 v22, -1, v21
	v_fma_f32 v23, -v22, v21, v20
	v_cmp_ge_f32_e64 s[0:1], 0, v23
	v_add_u32_e32 v23, 1, v21
	s_nop 0
	v_cndmask_b32_e64 v22, v21, v22, s[0:1]
	v_fma_f32 v21, -v23, v21, v20
	v_cmp_lt_f32_e64 s[0:1], 0, v21
	s_nop 1
	v_cndmask_b32_e64 v21, v22, v23, s[0:1]
	v_mul_f32_e32 v22, 0x37800000, v21
	v_cndmask_b32_e32 v21, v21, v22, vcc
	v_cmp_class_f32_e32 vcc, v20, v207
	s_nop 1
	v_cndmask_b32_e32 v20, v21, v20, vcc
	v_div_scale_f32 v21, s[0:1], v20, v20, 1.0
	v_rcp_f32_e32 v22, v21
	s_nop 0
	v_fma_f32 v23, -v21, v22, 1.0
	v_fmac_f32_e32 v22, v23, v22
	v_div_scale_f32 v23, vcc, 1.0, v20, 1.0
	v_mul_f32_e32 v24, v23, v22
	v_fma_f32 v25, -v21, v24, v23
	v_fmac_f32_e32 v24, v25, v22
	v_fma_f32 v21, -v21, v24, v23
	v_div_fmas_f32 v21, v21, v22, v24
	v_div_fixup_f32 v20, v21, v20, 1.0
	v_pk_mul_f32 v[22:23], v[12:13], v[20:21] op_sel_hi:[1,0]
	v_pk_mul_f32 v[12:13], v[10:11], v[20:21] op_sel_hi:[1,0]
	v_pk_mul_f32 v[16:17], v[16:17], v[20:21] op_sel_hi:[1,0]
	v_pk_mul_f32 v[14:15], v[14:15], v[20:21] op_sel_hi:[1,0]
	s_nop 0
	v_cvt_pk_bf16_f32 v10, v14, v15
	v_cvt_pk_bf16_f32 v11, v16, v17
	v_cvt_pk_bf16_f32 v12, v12, v13
	v_cvt_pk_bf16_f32 v13, v22, v23
	global_store_dwordx4 v[18:19], v[10:13], off
	s_cbranch_scc1 .LBB0_1306
	v_mov_b32_e32 v21, v20
	v_mov_b32_e32 v10, v20
	v_mov_b32_e32 v11, v20
	v_pk_mul_f32 v[8:9], v[8:9], v[10:11]
	v_pk_mul_f32 v[10:11], v[4:5], v[10:11]
	v_pk_mul_f32 v[4:5], v[2:3], v[20:21]
	v_pk_mul_f32 v[6:7], v[6:7], v[20:21]
	s_nop 0
	v_cvt_pk_bf16_f32 v2, v6, v7
	v_cvt_pk_bf16_f32 v3, v8, v9
	v_cvt_pk_bf16_f32 v4, v4, v5
	v_cvt_pk_bf16_f32 v5, v10, v11
	global_store_dwordx4 v[18:19], v[2:5], off offset:256
